# SwiGLU epilogues: per-panel 1/rms factors cached in spare VGPRs, fast-path epilogue copy skips the statistics loads/reduction when the row panel is unchanged (plus address cleanup and hand-off trim)
# speedup vs baseline: 1.0057x; 1.0026x over previous
.LBB0_238:
	s_add_u32 s70, s86, 0xac68000
	v_and_b32_e32 v136, 15, v0
	v_and_b32_e32 v2, 48, v0
	v_lshlrev_b32_e32 v4, 2, v0
	s_addc_u32 s71, s87, 0
	s_and_b32 s1, s18, 3
	s_lshl_b32 s72, s0, 6
	s_lshl_b32 s0, s0, 13
	v_lshl_or_b32 v3, v136, 6, v2
	v_and_b32_e32 v4, 32, v4
	v_lshlrev_b32_e32 v5, 6, v0
	s_movk_i32 s73, 0x3c0
	v_bitop3_b32 v3, v3, s0, v4 bitop3:0xde
	s_lshl_b32 s19, s18, 5
	s_lshl_b32 s0, s1, 12
	v_and_or_b32 v2, v5, s73, v2
	v_bitop3_b32 v2, s0, v2, v4 bitop3:0xf6
	s_add_u32 s0, s6, 0x8000
	s_waitcnt vmcnt(2)
	s_barrier
	s_addc_u32 s1, s7, 0
	s_add_i32 s74, s65, 0x18000
	s_mov_b32 m0, s74
	s_nop 0
	global_load_lds_dwordx4 v134, s[0:1]
	s_add_u32 m0, s74, 0x2000
	s_nop 0
	global_load_lds_dwordx4 v135, s[0:1]
	s_add_u32 s0, s12, 0x8000
	s_addc_u32 s1, s13, 0
	s_add_i32 s76, s65, 0x8000
	s_mov_b32 m0, s76
	s_nop 0
	global_load_lds_dwordx4 v134, s[0:1]
	s_add_u32 m0, s76, 0x2000
	s_nop 0
	global_load_lds_dwordx4 v135, s[0:1]
	s_add_u32 s0, s6, 0xc000
	s_addc_u32 s1, s7, 0
	s_add_i32 s77, s65, 0x1c000
	s_mov_b32 m0, s77
	s_nop 0
	global_load_lds_dwordx4 v134, s[0:1]
	s_add_u32 m0, s77, 0x2000
	s_nop 0
	global_load_lds_dwordx4 v135, s[0:1]
	s_add_i32 s78, s65, 0xc000
	s_cmpk_lt_u32 s16, 0x100
	s_cselect_b64 s[16:17], -1, 0
	s_bfe_u32 s79, s18, 0x10001
	s_and_b32 s80, s19, 32
	s_cmp_eq_u64 s[86:87], 0
	v_cmp_ne_u32_e64 s[42:43], 0, v196
	s_cselect_b64 s[18:19], -1, 0
	s_or_b64 s[18:19], s[42:43], s[18:19]
	s_ashr_i32 s81, s25, 31
	s_and_b32 s0, s25, 7
	s_ashr_i32 s82, s25, 3
	s_cmp_eq_u32 s82, 6
	s_cselect_b64 s[20:21], -1, 0
	s_sub_i32 s1, s82, 17
	s_waitcnt vmcnt(6)
	s_cmp_lt_u32 s1, 2
	s_cselect_b64 s[22:23], -1, 0
	s_lshl_b32 s83, s82, 5
	s_and_b32 s1, s25, 1
	v_add_u32_e32 v2, 0, v2
	s_addk_i32 s83, 0xff06
	s_or_b32 s44, s0, 0xfffff500
	s_or_b32 s45, s1, 0x80
	s_lshl_b32 s90, s0, 4
	s_mov_b32 s62, -1
	v_add_u32_e32 v137, 0x10000, v2
	v_add_u32_e32 v138, 0x14000, v2
	v_add_u32_e32 v139, 0, v3
	v_add_u32_e32 v140, 0x18000, v2
	v_add_u32_e32 v141, 0x1c000, v2
	v_mov_b32_e32 v131, 0
	v_mov_b32_e32 v142, 1
	v_mbcnt_hi_u32_b32 v143, -1, v211
	v_mov_b32_e32 v144, 0x358637bd
	s_mov_b32 s24, 0xbfb8aa3b
	v_mov_b64_e32 v[132:133], 0xb2b
	s_barrier
	s_mov_b32 s100, -1

.LBB0_259:
	s_cmp_eq_u32 s91, s100
	s_cbranch_scc0 .Lcr0_slow
	s_and_b64 vcc, exec, s[16:17]
	s_cbranch_vccz .Lcr0_261
	s_barrier
.Lcr0_261:
	v_mov_b32_e32 v130, v136
	v_mov_b32_e32 v145, v210
	v_readlane_b32 s0, v248, 15
	v_add_u32_e32 v130, s72, v130
	v_lshl_add_u32 v146, s91, 8, v130
	v_lshlrev_b32_e32 v148, 2, v145
	v_ashrrev_i32_e32 v149, 31, v148
	v_readlane_b32 s1, v248, 16
	v_ashrrev_i32_e32 v147, 31, v146
	v_lshlrev_b64 v[146:147], 6, v[146:147]
	v_lshl_add_u64 v[148:149], v[148:149], 2, s[0:1]
	v_lshl_add_u64 v[146:147], v[148:149], 0, v[146:147]
	s_nop 0
	s_mov_b32 s98, 0x1000
	s_mov_b32 s99, 0x0
	s_movk_i32 s0, 0x2000
	v_add_co_u32_e32 v146, vcc, s0, v146
	v_xor_b32_e32 v180, 32, v143
	s_nop 0
	v_addc_co_u32_e32 v147, vcc, 0, v147, vcc
	s_mov_b32 s98, 0x3000
	s_mov_b32 s99, 0x0
	s_nop 0
	v_and_b32_e32 v147, 64, v143
	v_xor_b32_e32 v146, 16, v143
	v_add_u32_e32 v147, 64, v147
	v_cmp_lt_i32_e32 vcc, v146, v147
	s_mul_i32 s0, s91, 44
	s_lshl_b32 s1, s10, 1
	s_nop 0
	v_cmp_lt_i32_e32 vcc, v180, v147
	s_nop 0
	s_add_i32 s0, s0, s1
	s_nop 0
	v_lshl_add_u32 v180, v145, 3, s80
	v_ashrrev_i32_e32 v146, 5, v180
	s_or_b32 s0, s0, s79
	s_ashr_i32 s1, s0, 31
	s_lshl_b64 s[0:1], s[0:1], 15
	v_lshlrev_b32_e32 v145, 4, v145
	s_add_u32 s50, s70, s0
	v_and_b32_e32 v145, 48, v145
	s_addc_u32 s51, s71, s1
	s_cmpk_lt_i32 s91, 0x80
	s_cselect_b64 s[0:1], -1, 0
	s_xor_b64 s[52:53], s[36:37], -1
	s_and_b64 s[52:53], s[52:53], s[0:1]
	s_mov_b64 s[6:7], -1
	s_and_b64 vcc, exec, s[52:53]
	s_waitcnt lgkmcnt(1)
	s_waitcnt lgkmcnt(0)
	s_waitcnt lgkmcnt(2)
	s_waitcnt lgkmcnt(4)
	s_waitcnt lgkmcnt(3)
	v_mov_b32_e32 v162, v244
	s_waitcnt lgkmcnt(3)
	s_waitcnt lgkmcnt(2)
	v_pk_mul_f32 v[122:123], v[122:123], v[162:163] op_sel_hi:[1,0]
	s_waitcnt lgkmcnt(1)
	v_pk_mul_f32 v[124:125], v[124:125], v[162:163] op_sel_hi:[1,0]
	v_pk_mul_f32 v[164:165], v[122:123], s[24:25] op_sel_hi:[1,0]
	s_waitcnt lgkmcnt(0)
	v_pk_mul_f32 v[166:167], v[124:125], s[24:25] op_sel_hi:[1,0]
	v_exp_f32_e32 v164, v164
	v_exp_f32_e32 v165, v165
	v_exp_f32_e32 v166, v166
	v_exp_f32_e32 v167, v167
	v_pk_mul_f32 v[126:127], v[126:127], v[162:163] op_sel_hi:[1,0]
	v_pk_add_f32 v[164:165], v[164:165], 1.0 op_sel_hi:[1,0]
	v_pk_mul_f32 v[114:115], v[114:115], v[162:163] op_sel_hi:[1,0]
	v_pk_add_f32 v[166:167], v[166:167], 1.0 op_sel_hi:[1,0]
	v_rcp_f32_e32 v164, v164
	v_rcp_f32_e32 v165, v165
	v_rcp_f32_e32 v166, v166
	v_rcp_f32_e32 v167, v167
	v_pk_mul_f32 v[128:129], v[128:129], v[162:163] op_sel_hi:[1,0]
	v_pk_mul_f32 v[122:123], v[122:123], v[164:165]
	v_pk_mul_f32 v[116:117], v[116:117], v[162:163] op_sel_hi:[1,0]
	v_pk_mul_f32 v[124:125], v[124:125], v[166:167]
	v_pk_mul_f32 v[122:123], v[126:127], v[122:123]
	v_pk_mul_f32 v[126:127], v[114:115], s[24:25] op_sel_hi:[1,0]
	v_pk_mul_f32 v[124:125], v[128:129], v[124:125]
	v_exp_f32_e32 v126, v126
	v_exp_f32_e32 v127, v127
	v_pk_mul_f32 v[128:129], v[116:117], s[24:25] op_sel_hi:[1,0]
	v_pk_mul_f32 v[118:119], v[118:119], v[162:163] op_sel_hi:[1,0]
	v_exp_f32_e32 v128, v128
	v_exp_f32_e32 v129, v129
	v_pk_add_f32 v[126:127], v[126:127], 1.0 op_sel_hi:[1,0]
	s_nop 0
	v_rcp_f32_e32 v126, v126
	v_rcp_f32_e32 v127, v127
	v_pk_add_f32 v[128:129], v[128:129], 1.0 op_sel_hi:[1,0]
	s_nop 0
	v_rcp_f32_e32 v128, v128
	v_rcp_f32_e32 v129, v129
	v_pk_mul_f32 v[114:115], v[114:115], v[126:127]
	s_nop 0
	v_pk_mul_f32 v[126:127], v[118:119], v[114:115]
	v_pk_mul_f32 v[114:115], v[120:121], v[162:163] op_sel_hi:[1,0]
	v_pk_mul_f32 v[116:117], v[116:117], v[128:129]
	v_pk_mul_f32 v[128:129], v[114:115], v[116:117]
	v_lshrrev_b32_e32 v115, 3, v130
	v_lshlrev_b32_e32 v114, 7, v130
	v_and_b32_e32 v115, 14, v115
	v_and_b32_e32 v114, 0xffffc000, v114
	v_lshlrev_b32_e32 v116, 6, v130
	v_add_lshl_u32 v120, v115, v146, 10
	v_lshlrev_b32_e32 v115, 2, v130
	v_and_or_b32 v116, v116, s73, v145
	v_and_b32_e32 v115, 32, v115
	v_add_u32_e32 v114, v120, v114
	v_bitop3_b32 v114, v114, v116, v115 bitop3:0xf6
	v_ashrrev_i32_e32 v115, 31, v114
	v_lshl_add_u64 v[118:119], s[50:51], 0, v[114:115]
	v_cvt_pk_bf16_f32 v114, v122, v123
	v_cvt_pk_bf16_f32 v115, v124, v125
	v_cvt_pk_bf16_f32 v116, v126, v127
	v_cvt_pk_bf16_f32 v117, v128, v129
	v_lshl_add_u64 v[184:185], v[118:119], 0, 0
	s_cbranch_vccz .Lcr0_263
	global_store_dwordx4 v[118:119], v[114:117], off
	s_mov_b64 s[6:7], 0

.Lcr0_265:
	s_waitcnt lgkmcnt(6)
	s_nop 0
	s_nop 0
	v_mov_b32_e32 v114, v245
	s_mov_b64 s[54:55], -1
	s_andn2_b64 vcc, exec, s[52:53]
	v_pk_mul_f32 v[106:107], v[106:107], v[114:115] op_sel_hi:[1,0]
	v_pk_mul_f32 v[110:111], v[110:111], v[114:115] op_sel_hi:[1,0]
	v_pk_mul_f32 v[116:117], v[106:107], s[24:25] op_sel_hi:[1,0]
	v_pk_mul_f32 v[108:109], v[108:109], v[114:115] op_sel_hi:[1,0]
	v_exp_f32_e32 v116, v116
	v_exp_f32_e32 v117, v117
	v_pk_mul_f32 v[98:99], v[98:99], v[114:115] op_sel_hi:[1,0]
	v_pk_mul_f32 v[102:103], v[102:103], v[114:115] op_sel_hi:[1,0]
	v_pk_add_f32 v[116:117], v[116:117], 1.0 op_sel_hi:[1,0]
	s_nop 0
	v_rcp_f32_e32 v116, v116
	v_rcp_f32_e32 v117, v117
	s_nop 0
	v_pk_mul_f32 v[106:107], v[106:107], v[116:117]
	s_nop 0
	v_pk_mul_f32 v[106:107], v[110:111], v[106:107]
	v_pk_mul_f32 v[110:111], v[112:113], v[114:115] op_sel_hi:[1,0]
	v_pk_mul_f32 v[112:113], v[108:109], s[24:25] op_sel_hi:[1,0]
	s_nop 0
	v_exp_f32_e32 v112, v112
	v_exp_f32_e32 v113, v113
	s_nop 0
	v_pk_add_f32 v[112:113], v[112:113], 1.0 op_sel_hi:[1,0]
	s_nop 0
	v_rcp_f32_e32 v112, v112
	v_rcp_f32_e32 v113, v113
	s_nop 0
	v_pk_mul_f32 v[108:109], v[108:109], v[112:113]
	s_nop 0
	v_pk_mul_f32 v[108:109], v[110:111], v[108:109]
	v_pk_mul_f32 v[110:111], v[98:99], s[24:25] op_sel_hi:[1,0]
	s_nop 0
	v_exp_f32_e32 v110, v110
	v_exp_f32_e32 v111, v111
	s_nop 0
	v_pk_add_f32 v[110:111], v[110:111], 1.0 op_sel_hi:[1,0]
	s_nop 0
	v_rcp_f32_e32 v110, v110
	v_rcp_f32_e32 v111, v111
	s_nop 0
	v_pk_mul_f32 v[98:99], v[98:99], v[110:111]
	s_nop 0
	v_pk_mul_f32 v[110:111], v[102:103], v[98:99]
	v_pk_mul_f32 v[98:99], v[100:101], v[114:115] op_sel_hi:[1,0]
	v_pk_mul_f32 v[100:101], v[104:105], v[114:115] op_sel_hi:[1,0]
	v_pk_mul_f32 v[102:103], v[98:99], s[24:25] op_sel_hi:[1,0]
	s_nop 0
	v_exp_f32_e32 v102, v102
	v_exp_f32_e32 v103, v103
	s_nop 0
	v_pk_add_f32 v[102:103], v[102:103], 1.0 op_sel_hi:[1,0]
	s_nop 0
	v_rcp_f32_e32 v102, v102
	v_rcp_f32_e32 v103, v103
	s_nop 0
	v_pk_mul_f32 v[98:99], v[98:99], v[102:103]
	s_nop 0
	v_pk_mul_f32 v[104:105], v[100:101], v[98:99]
	s_nop 0
	s_nop 0
	s_nop 0
	s_nop 0
	s_nop 0
	v_cvt_pk_bf16_f32 v101, v104, v105
	v_cndmask_b32_e64 v104, 0, 1, s[52:53]
	v_cvt_pk_bf16_f32 v98, v106, v107
	v_cvt_pk_bf16_f32 v99, v108, v109
	v_cvt_pk_bf16_f32 v100, v110, v111
	v_cmp_ne_u32_e64 s[6:7], 1, v104
	s_cbranch_vccnz .Lcr0_267
	s_mov_b64 s[54:55], 0
	global_store_dwordx4 v[186:187], v[98:101], off offset:-2048

.Lcr0_269:
	s_waitcnt lgkmcnt(5)
	s_nop 0
	s_nop 0
	v_mov_b32_e32 v98, v246
	s_mov_b64 s[52:53], -1
	s_and_b64 vcc, exec, s[6:7]
	v_pk_mul_f32 v[90:91], v[90:91], v[98:99] op_sel_hi:[1,0]
	v_pk_mul_f32 v[94:95], v[94:95], v[98:99] op_sel_hi:[1,0]
	v_pk_mul_f32 v[100:101], v[90:91], s[24:25] op_sel_hi:[1,0]
	v_pk_mul_f32 v[92:93], v[92:93], v[98:99] op_sel_hi:[1,0]
	v_exp_f32_e32 v100, v100
	v_exp_f32_e32 v101, v101
	v_pk_mul_f32 v[82:83], v[82:83], v[98:99] op_sel_hi:[1,0]
	v_pk_mul_f32 v[86:87], v[86:87], v[98:99] op_sel_hi:[1,0]
	v_pk_add_f32 v[100:101], v[100:101], 1.0 op_sel_hi:[1,0]
	s_nop 0
	v_rcp_f32_e32 v100, v100
	v_rcp_f32_e32 v101, v101
	s_nop 0
	v_pk_mul_f32 v[90:91], v[90:91], v[100:101]
	s_nop 0
	v_pk_mul_f32 v[90:91], v[94:95], v[90:91]
	v_pk_mul_f32 v[94:95], v[96:97], v[98:99] op_sel_hi:[1,0]
	v_pk_mul_f32 v[96:97], v[92:93], s[24:25] op_sel_hi:[1,0]
	s_nop 0
	v_exp_f32_e32 v96, v96
	v_exp_f32_e32 v97, v97
	s_nop 0
	v_pk_add_f32 v[96:97], v[96:97], 1.0 op_sel_hi:[1,0]
	s_nop 0
	v_rcp_f32_e32 v96, v96
	v_rcp_f32_e32 v97, v97
	s_nop 0
	v_pk_mul_f32 v[92:93], v[92:93], v[96:97]
	s_nop 0
	v_pk_mul_f32 v[92:93], v[94:95], v[92:93]
	v_pk_mul_f32 v[94:95], v[82:83], s[24:25] op_sel_hi:[1,0]
	s_nop 0
	v_exp_f32_e32 v94, v94
	v_exp_f32_e32 v95, v95
	s_nop 0
	v_pk_add_f32 v[94:95], v[94:95], 1.0 op_sel_hi:[1,0]
	s_nop 0
	v_rcp_f32_e32 v94, v94
	v_rcp_f32_e32 v95, v95
	s_nop 0
	v_pk_mul_f32 v[82:83], v[82:83], v[94:95]
	s_nop 0
	v_pk_mul_f32 v[94:95], v[86:87], v[82:83]
	v_pk_mul_f32 v[82:83], v[84:85], v[98:99] op_sel_hi:[1,0]
	v_pk_mul_f32 v[84:85], v[88:89], v[98:99] op_sel_hi:[1,0]
	v_pk_mul_f32 v[86:87], v[82:83], s[24:25] op_sel_hi:[1,0]
	s_nop 0
	v_exp_f32_e32 v86, v86
	v_exp_f32_e32 v87, v87
	s_nop 0
	v_pk_add_f32 v[86:87], v[86:87], 1.0 op_sel_hi:[1,0]
	s_nop 0
	v_rcp_f32_e32 v86, v86
	v_rcp_f32_e32 v87, v87
	s_nop 0
	v_pk_mul_f32 v[82:83], v[82:83], v[86:87]
	s_nop 0
	v_pk_mul_f32 v[88:89], v[84:85], v[82:83]
	s_nop 0
	v_cvt_pk_bf16_f32 v82, v90, v91
	v_cvt_pk_bf16_f32 v83, v92, v93
	v_cvt_pk_bf16_f32 v84, v94, v95
	v_cvt_pk_bf16_f32 v85, v88, v89
	s_cbranch_vccnz .Lcr0_271
	s_mov_b64 s[52:53], 0
	global_store_dwordx4 v[186:187], v[82:85], off

.Lcr0_273:
	s_waitcnt lgkmcnt(4)
	s_nop 0
	s_nop 0
	v_mov_b32_e32 v82, v247
	s_mov_b64 s[52:53], -1
	s_and_b64 vcc, exec, s[6:7]
	v_pk_mul_f32 v[74:75], v[74:75], v[82:83] op_sel_hi:[1,0]
	v_pk_mul_f32 v[78:79], v[78:79], v[82:83] op_sel_hi:[1,0]
	v_pk_mul_f32 v[84:85], v[74:75], s[24:25] op_sel_hi:[1,0]
	v_pk_mul_f32 v[76:77], v[76:77], v[82:83] op_sel_hi:[1,0]
	v_exp_f32_e32 v84, v84
	v_exp_f32_e32 v85, v85
	v_pk_mul_f32 v[66:67], v[66:67], v[82:83] op_sel_hi:[1,0]
	v_pk_mul_f32 v[70:71], v[70:71], v[82:83] op_sel_hi:[1,0]
	v_pk_add_f32 v[84:85], v[84:85], 1.0 op_sel_hi:[1,0]
	s_nop 0
	v_rcp_f32_e32 v84, v84
	v_rcp_f32_e32 v85, v85
	s_nop 0
	v_pk_mul_f32 v[74:75], v[74:75], v[84:85]
	s_nop 0
	v_pk_mul_f32 v[74:75], v[78:79], v[74:75]
	v_pk_mul_f32 v[78:79], v[80:81], v[82:83] op_sel_hi:[1,0]
	v_pk_mul_f32 v[80:81], v[76:77], s[24:25] op_sel_hi:[1,0]
	s_nop 0
	v_exp_f32_e32 v80, v80
	v_exp_f32_e32 v81, v81
	s_nop 0
	v_pk_add_f32 v[80:81], v[80:81], 1.0 op_sel_hi:[1,0]
	s_nop 0
	v_rcp_f32_e32 v80, v80
	v_rcp_f32_e32 v81, v81
	s_nop 0
	v_pk_mul_f32 v[76:77], v[76:77], v[80:81]
	s_nop 0
	v_pk_mul_f32 v[76:77], v[78:79], v[76:77]
	v_pk_mul_f32 v[78:79], v[66:67], s[24:25] op_sel_hi:[1,0]
	s_nop 0
	v_exp_f32_e32 v78, v78
	v_exp_f32_e32 v79, v79
	s_nop 0
	v_pk_add_f32 v[78:79], v[78:79], 1.0 op_sel_hi:[1,0]
	s_nop 0
	v_rcp_f32_e32 v78, v78
	v_rcp_f32_e32 v79, v79
	s_nop 0
	v_pk_mul_f32 v[66:67], v[66:67], v[78:79]
	s_nop 0
	v_pk_mul_f32 v[78:79], v[70:71], v[66:67]
	v_pk_mul_f32 v[66:67], v[68:69], v[82:83] op_sel_hi:[1,0]
	v_pk_mul_f32 v[68:69], v[72:73], v[82:83] op_sel_hi:[1,0]
	v_pk_mul_f32 v[70:71], v[66:67], s[24:25] op_sel_hi:[1,0]
	s_nop 0
	v_exp_f32_e32 v70, v70
	v_exp_f32_e32 v71, v71
	s_nop 0
	v_pk_add_f32 v[70:71], v[70:71], 1.0 op_sel_hi:[1,0]
	s_nop 0
	v_rcp_f32_e32 v70, v70
	v_rcp_f32_e32 v71, v71
	s_nop 0
	v_pk_mul_f32 v[66:67], v[66:67], v[70:71]
	s_nop 0
	v_pk_mul_f32 v[72:73], v[68:69], v[66:67]
	s_nop 0
	v_cvt_pk_bf16_f32 v66, v74, v75
	v_cvt_pk_bf16_f32 v67, v76, v77
	v_cvt_pk_bf16_f32 v68, v78, v79
	v_cvt_pk_bf16_f32 v69, v72, v73
	s_cbranch_vccnz .Lcr0_275
	s_mov_b64 s[52:53], 0
	global_store_dwordx4 v[186:187], v[66:69], off offset:2048

.Lcr0_277:
	s_waitcnt lgkmcnt(3)
	s_nop 0
	s_nop 0
	v_mov_b32_e32 v66, v250
	s_nop 0
	s_mov_b64 s[52:53], -1
	v_pk_mul_f32 v[58:59], v[58:59], v[66:67] op_sel_hi:[1,0]
	v_pk_mul_f32 v[62:63], v[62:63], v[66:67] op_sel_hi:[1,0]
	v_pk_mul_f32 v[68:69], v[58:59], s[24:25] op_sel_hi:[1,0]
	v_pk_mul_f32 v[60:61], v[60:61], v[66:67] op_sel_hi:[1,0]
	v_exp_f32_e32 v68, v68
	v_exp_f32_e32 v69, v69
	v_pk_mul_f32 v[50:51], v[50:51], v[66:67] op_sel_hi:[1,0]
	v_pk_mul_f32 v[54:55], v[54:55], v[66:67] op_sel_hi:[1,0]
	s_and_b64 vcc, exec, s[6:7]
	v_pk_add_f32 v[68:69], v[68:69], 1.0 op_sel_hi:[1,0]
	s_nop 0
	v_rcp_f32_e32 v68, v68
	v_rcp_f32_e32 v69, v69
	s_nop 0
	v_pk_mul_f32 v[58:59], v[58:59], v[68:69]
	s_nop 0
	v_pk_mul_f32 v[58:59], v[62:63], v[58:59]
	v_pk_mul_f32 v[62:63], v[64:65], v[66:67] op_sel_hi:[1,0]
	v_pk_mul_f32 v[64:65], v[60:61], s[24:25] op_sel_hi:[1,0]
	s_nop 0
	v_exp_f32_e32 v64, v64
	v_exp_f32_e32 v65, v65
	s_nop 0
	v_pk_add_f32 v[64:65], v[64:65], 1.0 op_sel_hi:[1,0]
	s_nop 0
	v_rcp_f32_e32 v64, v64
	v_rcp_f32_e32 v65, v65
	s_nop 0
	v_pk_mul_f32 v[60:61], v[60:61], v[64:65]
	s_nop 0
	v_pk_mul_f32 v[60:61], v[62:63], v[60:61]
	v_pk_mul_f32 v[62:63], v[50:51], s[24:25] op_sel_hi:[1,0]
	s_nop 0
	v_exp_f32_e32 v62, v62
	v_exp_f32_e32 v63, v63
	s_nop 0
	v_pk_add_f32 v[62:63], v[62:63], 1.0 op_sel_hi:[1,0]
	s_nop 0
	v_rcp_f32_e32 v62, v62
	v_rcp_f32_e32 v63, v63
	s_nop 0
	v_pk_mul_f32 v[50:51], v[50:51], v[62:63]
	s_nop 0
	v_pk_mul_f32 v[62:63], v[54:55], v[50:51]
	v_pk_mul_f32 v[50:51], v[52:53], v[66:67] op_sel_hi:[1,0]
	v_pk_mul_f32 v[52:53], v[56:57], v[66:67] op_sel_hi:[1,0]
	v_pk_mul_f32 v[54:55], v[50:51], s[24:25] op_sel_hi:[1,0]
	s_nop 0
	v_exp_f32_e32 v54, v54
	v_exp_f32_e32 v55, v55
	s_nop 0
	v_pk_add_f32 v[54:55], v[54:55], 1.0 op_sel_hi:[1,0]
	s_nop 0
	v_rcp_f32_e32 v54, v54
	v_rcp_f32_e32 v55, v55
	s_nop 0
	v_pk_mul_f32 v[50:51], v[50:51], v[54:55]
	s_nop 0
	v_pk_mul_f32 v[56:57], v[52:53], v[50:51]
	s_nop 0
	v_cvt_pk_bf16_f32 v50, v58, v59
	v_cvt_pk_bf16_f32 v51, v60, v61
	v_cvt_pk_bf16_f32 v52, v62, v63
	v_cvt_pk_bf16_f32 v53, v56, v57
	s_mov_b32 s98, 0x5000
	s_mov_b32 s99, 0x0
	v_lshl_add_u64 v[186:187], v[184:185], 0, s[98:99]
	s_cbranch_vccnz .Lcr0_279
	s_mov_b64 s[52:53], 0
	global_store_dwordx4 v[186:187], v[50:53], off offset:-4096

.Lcr0_281:
	s_waitcnt lgkmcnt(2)
	s_nop 0
	s_nop 0
	v_mov_b32_e32 v50, v251
	s_mov_b64 s[52:53], -1
	s_and_b64 vcc, exec, s[6:7]
	v_pk_mul_f32 v[42:43], v[42:43], v[50:51] op_sel_hi:[1,0]
	v_pk_mul_f32 v[46:47], v[46:47], v[50:51] op_sel_hi:[1,0]
	v_pk_mul_f32 v[52:53], v[42:43], s[24:25] op_sel_hi:[1,0]
	v_pk_mul_f32 v[44:45], v[44:45], v[50:51] op_sel_hi:[1,0]
	v_exp_f32_e32 v52, v52
	v_exp_f32_e32 v53, v53
	v_pk_mul_f32 v[34:35], v[34:35], v[50:51] op_sel_hi:[1,0]
	v_pk_mul_f32 v[38:39], v[38:39], v[50:51] op_sel_hi:[1,0]
	v_pk_add_f32 v[52:53], v[52:53], 1.0 op_sel_hi:[1,0]
	s_nop 0
	v_rcp_f32_e32 v52, v52
	v_rcp_f32_e32 v53, v53
	s_nop 0
	v_pk_mul_f32 v[42:43], v[42:43], v[52:53]
	s_nop 0
	v_pk_mul_f32 v[42:43], v[46:47], v[42:43]
	v_pk_mul_f32 v[46:47], v[48:49], v[50:51] op_sel_hi:[1,0]
	v_pk_mul_f32 v[48:49], v[44:45], s[24:25] op_sel_hi:[1,0]
	s_nop 0
	v_exp_f32_e32 v48, v48
	v_exp_f32_e32 v49, v49
	s_nop 0
	v_pk_add_f32 v[48:49], v[48:49], 1.0 op_sel_hi:[1,0]
	s_nop 0
	v_rcp_f32_e32 v48, v48
	v_rcp_f32_e32 v49, v49
	s_nop 0
	v_pk_mul_f32 v[44:45], v[44:45], v[48:49]
	s_nop 0
	v_pk_mul_f32 v[44:45], v[46:47], v[44:45]
	v_pk_mul_f32 v[46:47], v[34:35], s[24:25] op_sel_hi:[1,0]
	s_nop 0
	v_exp_f32_e32 v46, v46
	v_exp_f32_e32 v47, v47
	s_nop 0
	v_pk_add_f32 v[46:47], v[46:47], 1.0 op_sel_hi:[1,0]
	s_nop 0
	v_rcp_f32_e32 v46, v46
	v_rcp_f32_e32 v47, v47
	s_nop 0
	v_pk_mul_f32 v[34:35], v[34:35], v[46:47]
	s_nop 0
	v_pk_mul_f32 v[46:47], v[38:39], v[34:35]
	v_pk_mul_f32 v[34:35], v[36:37], v[50:51] op_sel_hi:[1,0]
	v_pk_mul_f32 v[36:37], v[40:41], v[50:51] op_sel_hi:[1,0]
	v_pk_mul_f32 v[38:39], v[34:35], s[24:25] op_sel_hi:[1,0]
	s_nop 0
	v_exp_f32_e32 v38, v38
	v_exp_f32_e32 v39, v39
	s_nop 0
	v_pk_add_f32 v[38:39], v[38:39], 1.0 op_sel_hi:[1,0]
	s_nop 0
	v_rcp_f32_e32 v38, v38
	v_rcp_f32_e32 v39, v39
	s_nop 0
	v_pk_mul_f32 v[34:35], v[34:35], v[38:39]
	s_nop 0
	v_pk_mul_f32 v[40:41], v[36:37], v[34:35]
	s_nop 0
	v_cvt_pk_bf16_f32 v34, v42, v43
	v_cvt_pk_bf16_f32 v35, v44, v45
	v_cvt_pk_bf16_f32 v36, v46, v47
	v_cvt_pk_bf16_f32 v37, v40, v41
	s_cbranch_vccnz .Lcr0_283
	s_mov_b64 s[52:53], 0
	global_store_dwordx4 v[186:187], v[34:37], off offset:-2048

.Lcr0_285:
	s_waitcnt lgkmcnt(1)
	s_nop 0
	s_nop 0
	v_mov_b32_e32 v34, v252
	s_mov_b64 s[52:53], -1
	s_and_b64 vcc, exec, s[6:7]
	v_pk_mul_f32 v[26:27], v[26:27], v[34:35] op_sel_hi:[1,0]
	v_pk_mul_f32 v[30:31], v[30:31], v[34:35] op_sel_hi:[1,0]
	v_pk_mul_f32 v[36:37], v[26:27], s[24:25] op_sel_hi:[1,0]
	v_pk_mul_f32 v[28:29], v[28:29], v[34:35] op_sel_hi:[1,0]
	v_exp_f32_e32 v36, v36
	v_exp_f32_e32 v37, v37
	v_pk_mul_f32 v[18:19], v[18:19], v[34:35] op_sel_hi:[1,0]
	v_pk_mul_f32 v[22:23], v[22:23], v[34:35] op_sel_hi:[1,0]
	v_pk_add_f32 v[36:37], v[36:37], 1.0 op_sel_hi:[1,0]
	s_nop 0
	v_rcp_f32_e32 v36, v36
	v_rcp_f32_e32 v37, v37
	s_nop 0
	v_pk_mul_f32 v[26:27], v[26:27], v[36:37]
	s_nop 0
	v_pk_mul_f32 v[26:27], v[30:31], v[26:27]
	v_pk_mul_f32 v[30:31], v[32:33], v[34:35] op_sel_hi:[1,0]
	v_pk_mul_f32 v[32:33], v[28:29], s[24:25] op_sel_hi:[1,0]
	s_nop 0
	v_exp_f32_e32 v32, v32
	v_exp_f32_e32 v33, v33
	s_nop 0
	v_pk_add_f32 v[32:33], v[32:33], 1.0 op_sel_hi:[1,0]
	s_nop 0
	v_rcp_f32_e32 v32, v32
	v_rcp_f32_e32 v33, v33
	s_nop 0
	v_pk_mul_f32 v[28:29], v[28:29], v[32:33]
	s_nop 0
	v_pk_mul_f32 v[28:29], v[30:31], v[28:29]
	v_pk_mul_f32 v[30:31], v[18:19], s[24:25] op_sel_hi:[1,0]
	s_nop 0
	v_exp_f32_e32 v30, v30
	v_exp_f32_e32 v31, v31
	s_nop 0
	v_pk_add_f32 v[30:31], v[30:31], 1.0 op_sel_hi:[1,0]
	s_nop 0
	v_rcp_f32_e32 v30, v30
	v_rcp_f32_e32 v31, v31
	s_nop 0
	v_pk_mul_f32 v[18:19], v[18:19], v[30:31]
	s_nop 0
	v_pk_mul_f32 v[30:31], v[22:23], v[18:19]
	v_pk_mul_f32 v[18:19], v[20:21], v[34:35] op_sel_hi:[1,0]
	v_pk_mul_f32 v[20:21], v[24:25], v[34:35] op_sel_hi:[1,0]
	v_pk_mul_f32 v[22:23], v[18:19], s[24:25] op_sel_hi:[1,0]
	s_nop 0
	v_exp_f32_e32 v22, v22
	v_exp_f32_e32 v23, v23
	s_nop 0
	v_pk_add_f32 v[22:23], v[22:23], 1.0 op_sel_hi:[1,0]
	s_nop 0
	v_rcp_f32_e32 v22, v22
	v_rcp_f32_e32 v23, v23
	s_nop 0
	v_pk_mul_f32 v[18:19], v[18:19], v[22:23]
	s_nop 0
	v_pk_mul_f32 v[24:25], v[20:21], v[18:19]
	s_nop 0
	v_cvt_pk_bf16_f32 v18, v26, v27
	v_cvt_pk_bf16_f32 v19, v28, v29
	v_cvt_pk_bf16_f32 v20, v30, v31
	v_cvt_pk_bf16_f32 v21, v24, v25
	s_cbranch_vccnz .Lcr0_287
	s_mov_b64 s[52:53], 0
	global_store_dwordx4 v[186:187], v[18:21], off

.Lcr0_289:
	s_waitcnt lgkmcnt(0)
	s_nop 0
	s_nop 0
	v_mov_b32_e32 v18, v253
	s_and_b64 vcc, exec, s[6:7]
	v_pk_mul_f32 v[10:11], v[10:11], v[18:19] op_sel_hi:[1,0]
	s_nop 0
	v_pk_mul_f32 v[20:21], v[10:11], s[24:25] op_sel_hi:[1,0]
	v_pk_mul_f32 v[14:15], v[14:15], v[18:19] op_sel_hi:[1,0]
	v_exp_f32_e32 v20, v20
	v_exp_f32_e32 v21, v21
	v_pk_mul_f32 v[12:13], v[12:13], v[18:19] op_sel_hi:[1,0]
	v_pk_mul_f32 v[2:3], v[2:3], v[18:19] op_sel_hi:[1,0]
	v_pk_mul_f32 v[6:7], v[6:7], v[18:19] op_sel_hi:[1,0]
	v_pk_add_f32 v[20:21], v[20:21], 1.0 op_sel_hi:[1,0]
	s_nop 0
	v_rcp_f32_e32 v20, v20
	v_rcp_f32_e32 v21, v21
	s_nop 0
	v_pk_mul_f32 v[10:11], v[10:11], v[20:21]
	s_nop 0
	v_pk_mul_f32 v[10:11], v[14:15], v[10:11]
	v_pk_mul_f32 v[14:15], v[16:17], v[18:19] op_sel_hi:[1,0]
	v_pk_mul_f32 v[16:17], v[12:13], s[24:25] op_sel_hi:[1,0]
	s_nop 0
	v_exp_f32_e32 v16, v16
	v_exp_f32_e32 v17, v17
	s_nop 0
	v_pk_add_f32 v[16:17], v[16:17], 1.0 op_sel_hi:[1,0]
	s_nop 0
	v_rcp_f32_e32 v16, v16
	v_rcp_f32_e32 v17, v17
	s_nop 0
	v_pk_mul_f32 v[12:13], v[12:13], v[16:17]
	s_nop 0
	v_pk_mul_f32 v[12:13], v[14:15], v[12:13]
	v_pk_mul_f32 v[14:15], v[2:3], s[24:25] op_sel_hi:[1,0]
	s_nop 0
	v_exp_f32_e32 v14, v14
	v_exp_f32_e32 v15, v15
	s_nop 0
	v_pk_add_f32 v[14:15], v[14:15], 1.0 op_sel_hi:[1,0]
	s_nop 0
	v_rcp_f32_e32 v14, v14
	v_rcp_f32_e32 v15, v15
	s_nop 0
	v_pk_mul_f32 v[2:3], v[2:3], v[14:15]
	s_nop 0
	v_pk_mul_f32 v[14:15], v[6:7], v[2:3]
	v_pk_mul_f32 v[2:3], v[4:5], v[18:19] op_sel_hi:[1,0]
	v_pk_mul_f32 v[4:5], v[8:9], v[18:19] op_sel_hi:[1,0]
	v_pk_mul_f32 v[6:7], v[2:3], s[24:25] op_sel_hi:[1,0]
	s_nop 0
	v_exp_f32_e32 v6, v6
	v_exp_f32_e32 v7, v7
	s_nop 0
	v_pk_add_f32 v[6:7], v[6:7], 1.0 op_sel_hi:[1,0]
	s_nop 0
	v_rcp_f32_e32 v6, v6
	v_rcp_f32_e32 v7, v7
	s_nop 0
	v_pk_mul_f32 v[2:3], v[2:3], v[6:7]
	s_nop 0
	v_pk_mul_f32 v[8:9], v[4:5], v[2:3]
	s_nop 0
	v_cvt_pk_bf16_f32 v2, v10, v11
	v_cvt_pk_bf16_f32 v3, v12, v13
	v_cvt_pk_bf16_f32 v4, v14, v15
	v_cvt_pk_bf16_f32 v5, v8, v9
	s_mov_b64 s[50:51], -1
	s_cbranch_vccnz .Lcr0_291
	s_mov_b64 s[50:51], 0
	global_store_dwordx4 v[186:187], v[2:5], off offset:2048
.Lcr0_291:
	s_andn2_b64 vcc, exec, s[50:51]
	s_cbranch_vccnz .LBB0_293
	global_store_dwordx4 v[186:187], v[2:5], off offset:2048 sc1
	s_nop 1
	s_branch .LBB0_293
.Lcr0_slow:
	s_mov_b32 s100, s91
	s_and_b64 vcc, exec, s[16:17]
	s_cbranch_vccz .LBB0_261
	s_barrier
.LBB0_261:
	v_mov_b32_e32 v130, v136
	v_mov_b32_e32 v145, v210
	v_readlane_b32 s0, v248, 15
	v_add_u32_e32 v130, s72, v130
	v_lshl_add_u32 v146, s91, 8, v130
	v_lshlrev_b32_e32 v148, 2, v145
	v_ashrrev_i32_e32 v149, 31, v148
	v_readlane_b32 s1, v248, 16
	v_ashrrev_i32_e32 v147, 31, v146
	v_lshlrev_b64 v[146:147], 6, v[146:147]
	v_lshl_add_u64 v[148:149], v[148:149], 2, s[0:1]
	v_lshl_add_u64 v[146:147], v[148:149], 0, v[146:147]
	v_lshl_add_u64 v[184:185], v[146:147], 0, 0
	global_load_dwordx4 v[148:151], v[146:147], off
	s_mov_b32 s98, 0x1000
	s_mov_b32 s99, 0x0
	v_lshl_add_u64 v[186:187], v[184:185], 0, s[98:99]
	global_load_dwordx4 v[152:155], v[186:187], off offset:-3072
	global_load_dwordx4 v[156:159], v[186:187], off offset:-2048
	global_load_dwordx4 v[160:163], v[186:187], off offset:-1024
	s_movk_i32 s0, 0x2000
	v_add_co_u32_e32 v146, vcc, s0, v146
	v_xor_b32_e32 v180, 32, v143
	s_nop 0
	v_addc_co_u32_e32 v147, vcc, 0, v147, vcc
	s_mov_b32 s98, 0x3000
	s_mov_b32 s99, 0x0
	v_lshl_add_u64 v[186:187], v[184:185], 0, s[98:99]
	global_load_dwordx4 v[164:167], v[186:187], off offset:-4096
	global_load_dwordx4 v[168:171], v[186:187], off offset:-3072
	global_load_dwordx4 v[172:175], v[186:187], off offset:-2048
	global_load_dwordx4 v[176:179], v[186:187], off offset:-1024
	v_and_b32_e32 v147, 64, v143
	v_xor_b32_e32 v146, 16, v143
	v_add_u32_e32 v147, 64, v147
	v_cmp_lt_i32_e32 vcc, v146, v147
	s_mul_i32 s0, s91, 44
	s_lshl_b32 s1, s10, 1
	v_cndmask_b32_e32 v146, v143, v146, vcc
	v_cmp_lt_i32_e32 vcc, v180, v147
	v_lshlrev_b32_e32 v182, 2, v146
	s_add_i32 s0, s0, s1
	v_cndmask_b32_e32 v147, v143, v180, vcc
	v_lshl_add_u32 v180, v145, 3, s80
	v_ashrrev_i32_e32 v146, 5, v180
	v_lshlrev_b32_e32 v183, 2, v147
	s_or_b32 s0, s0, s79
	s_ashr_i32 s1, s0, 31
	s_lshl_b64 s[0:1], s[0:1], 15
	v_lshlrev_b32_e32 v145, 4, v145
	s_add_u32 s50, s70, s0
	v_and_b32_e32 v145, 48, v145
	s_addc_u32 s51, s71, s1
	s_cmpk_lt_i32 s91, 0x80
	s_cselect_b64 s[0:1], -1, 0
	s_xor_b64 s[52:53], s[36:37], -1
	s_and_b64 s[52:53], s[52:53], s[0:1]
	s_mov_b64 s[6:7], -1
	s_and_b64 vcc, exec, s[52:53]
	s_waitcnt vmcnt(7)
	v_mov_b32_e32 v180, v149
	v_mov_b32_e32 v181, v150
	v_mov_b32_e32 v149, v151
	s_waitcnt vmcnt(6)
	v_add_f32_e32 v147, v152, v153
	v_add_f32_e32 v150, v154, v155
	s_waitcnt vmcnt(5)
	v_add_f32_e32 v151, v156, v157
	v_add_f32_e32 v152, v158, v159
	s_waitcnt vmcnt(4)
	v_add_f32_e32 v153, v160, v161
	v_add_f32_e32 v154, v162, v163
	v_pk_add_f32 v[148:149], v[180:181], v[148:149]
	v_add_f32_e32 v147, v147, v150
	v_add_f32_e32 v150, v151, v152
	v_add_f32_e32 v151, v153, v154
	s_waitcnt vmcnt(3)
	v_add_f32_e32 v152, v164, v165
	v_add_f32_e32 v153, v166, v167
	v_add_f32_e32 v148, v148, v149
	v_add_f32_e32 v152, v152, v153
	ds_bpermute_b32 v153, v182, v148
	ds_bpermute_b32 v160, v182, v150
	s_waitcnt vmcnt(1)
	v_add_f32_e32 v156, v172, v173
	v_add_f32_e32 v157, v174, v175
	v_add_f32_e32 v162, v156, v157
	s_waitcnt lgkmcnt(1)
	v_add_f32_e32 v148, v148, v153
	s_waitcnt lgkmcnt(0)
	v_add_f32_e32 v157, v150, v160
	ds_bpermute_b32 v150, v183, v148
	ds_bpermute_b32 v149, v182, v147
	ds_bpermute_b32 v166, v182, v162
	v_add_f32_e32 v154, v168, v169
	v_add_f32_e32 v155, v170, v171
	s_waitcnt lgkmcnt(2)
	v_add_f32_e32 v148, v148, v150
	s_waitcnt vmcnt(0)
	v_add_f32_e32 v158, v176, v177
	v_add_f32_e32 v159, v178, v179
	v_add_f32_e32 v154, v154, v155
	v_fmamk_f32 v148, v148, 0x3a800000, v144
	ds_bpermute_b32 v161, v182, v151
	v_add_f32_e32 v163, v158, v159
	ds_bpermute_b32 v164, v182, v152
	ds_bpermute_b32 v165, v182, v154
	s_waitcnt lgkmcnt(4)
	v_add_f32_e32 v159, v147, v149
	s_waitcnt lgkmcnt(3)
	v_add_f32_e32 v149, v162, v166
	v_rsq_f32_e32 v162, v148
	ds_bpermute_b32 v167, v182, v163
	s_waitcnt lgkmcnt(3)
	v_add_f32_e32 v155, v151, v161
	s_waitcnt lgkmcnt(2)
	v_add_f32_e32 v153, v152, v164
	v_mov_b32_e32 v244, v162
	v_pk_mul_f32 v[122:123], v[122:123], v[162:163] op_sel_hi:[1,0]
	s_waitcnt lgkmcnt(1)
	v_add_f32_e32 v151, v154, v165
	v_pk_mul_f32 v[124:125], v[124:125], v[162:163] op_sel_hi:[1,0]
	v_pk_mul_f32 v[164:165], v[122:123], s[24:25] op_sel_hi:[1,0]
	s_waitcnt lgkmcnt(0)
	v_add_f32_e32 v147, v163, v167
	v_pk_mul_f32 v[166:167], v[124:125], s[24:25] op_sel_hi:[1,0]
	v_exp_f32_e32 v164, v164
	v_exp_f32_e32 v165, v165
	v_exp_f32_e32 v166, v166
	v_exp_f32_e32 v167, v167
	v_pk_mul_f32 v[126:127], v[126:127], v[162:163] op_sel_hi:[1,0]
	v_pk_add_f32 v[164:165], v[164:165], 1.0 op_sel_hi:[1,0]
	v_pk_mul_f32 v[114:115], v[114:115], v[162:163] op_sel_hi:[1,0]
	v_pk_add_f32 v[166:167], v[166:167], 1.0 op_sel_hi:[1,0]
	v_rcp_f32_e32 v164, v164
	v_rcp_f32_e32 v165, v165
	v_rcp_f32_e32 v166, v166
	v_rcp_f32_e32 v167, v167
	v_pk_mul_f32 v[128:129], v[128:129], v[162:163] op_sel_hi:[1,0]
	v_pk_mul_f32 v[122:123], v[122:123], v[164:165]
	v_pk_mul_f32 v[116:117], v[116:117], v[162:163] op_sel_hi:[1,0]
	v_pk_mul_f32 v[124:125], v[124:125], v[166:167]
	v_pk_mul_f32 v[122:123], v[126:127], v[122:123]
	v_pk_mul_f32 v[126:127], v[114:115], s[24:25] op_sel_hi:[1,0]
	v_pk_mul_f32 v[124:125], v[128:129], v[124:125]
	v_exp_f32_e32 v126, v126
	v_exp_f32_e32 v127, v127
	v_pk_mul_f32 v[128:129], v[116:117], s[24:25] op_sel_hi:[1,0]
	v_pk_mul_f32 v[118:119], v[118:119], v[162:163] op_sel_hi:[1,0]
	v_exp_f32_e32 v128, v128
	v_exp_f32_e32 v129, v129
	v_pk_add_f32 v[126:127], v[126:127], 1.0 op_sel_hi:[1,0]
	ds_bpermute_b32 v160, v183, v159
	v_rcp_f32_e32 v126, v126
	v_rcp_f32_e32 v127, v127
	v_pk_add_f32 v[128:129], v[128:129], 1.0 op_sel_hi:[1,0]
	ds_bpermute_b32 v158, v183, v157
	v_rcp_f32_e32 v128, v128
	v_rcp_f32_e32 v129, v129
	v_pk_mul_f32 v[114:115], v[114:115], v[126:127]
	ds_bpermute_b32 v156, v183, v155
	v_pk_mul_f32 v[126:127], v[118:119], v[114:115]
	v_pk_mul_f32 v[114:115], v[120:121], v[162:163] op_sel_hi:[1,0]
	v_pk_mul_f32 v[116:117], v[116:117], v[128:129]
	ds_bpermute_b32 v154, v183, v153
	v_pk_mul_f32 v[128:129], v[114:115], v[116:117]
	v_lshrrev_b32_e32 v115, 3, v130
	v_lshlrev_b32_e32 v114, 7, v130
	v_and_b32_e32 v115, 14, v115
	ds_bpermute_b32 v152, v183, v151
	ds_bpermute_b32 v150, v183, v149
	ds_bpermute_b32 v148, v183, v147
	v_and_b32_e32 v114, 0xffffc000, v114
	v_lshlrev_b32_e32 v116, 6, v130
	v_add_lshl_u32 v120, v115, v146, 10
	v_lshlrev_b32_e32 v115, 2, v130
	v_and_or_b32 v116, v116, s73, v145
	v_and_b32_e32 v115, 32, v115
	v_add_u32_e32 v114, v120, v114
	v_bitop3_b32 v114, v114, v116, v115 bitop3:0xf6
	v_ashrrev_i32_e32 v115, 31, v114
	v_lshl_add_u64 v[118:119], s[50:51], 0, v[114:115]
	v_cvt_pk_bf16_f32 v114, v122, v123
	v_cvt_pk_bf16_f32 v115, v124, v125
	v_cvt_pk_bf16_f32 v116, v126, v127
	v_cvt_pk_bf16_f32 v117, v128, v129
	v_lshl_add_u64 v[184:185], v[118:119], 0, 0
	s_cbranch_vccz .LBB0_263
	global_store_dwordx4 v[118:119], v[114:117], off
	s_mov_b64 s[6:7], 0

.LBB0_265:
	s_waitcnt lgkmcnt(6)
	v_add_f32_e32 v114, v159, v160
	v_fmamk_f32 v114, v114, 0x3a800000, v144
	v_rsq_f32_e32 v114, v114
	s_mov_b64 s[54:55], -1
	s_andn2_b64 vcc, exec, s[52:53]
	v_mov_b32_e32 v245, v114
	v_pk_mul_f32 v[106:107], v[106:107], v[114:115] op_sel_hi:[1,0]
	v_pk_mul_f32 v[110:111], v[110:111], v[114:115] op_sel_hi:[1,0]
	v_pk_mul_f32 v[116:117], v[106:107], s[24:25] op_sel_hi:[1,0]
	v_pk_mul_f32 v[108:109], v[108:109], v[114:115] op_sel_hi:[1,0]
	v_exp_f32_e32 v116, v116
	v_exp_f32_e32 v117, v117
	v_pk_mul_f32 v[98:99], v[98:99], v[114:115] op_sel_hi:[1,0]
	v_pk_mul_f32 v[102:103], v[102:103], v[114:115] op_sel_hi:[1,0]
	v_pk_add_f32 v[116:117], v[116:117], 1.0 op_sel_hi:[1,0]
	s_nop 0
	v_rcp_f32_e32 v116, v116
	v_rcp_f32_e32 v117, v117
	s_nop 0
	v_pk_mul_f32 v[106:107], v[106:107], v[116:117]
	s_nop 0
	v_pk_mul_f32 v[106:107], v[110:111], v[106:107]
	v_pk_mul_f32 v[110:111], v[112:113], v[114:115] op_sel_hi:[1,0]
	v_pk_mul_f32 v[112:113], v[108:109], s[24:25] op_sel_hi:[1,0]
	s_nop 0
	v_exp_f32_e32 v112, v112
	v_exp_f32_e32 v113, v113
	s_nop 0
	v_pk_add_f32 v[112:113], v[112:113], 1.0 op_sel_hi:[1,0]
	s_nop 0
	v_rcp_f32_e32 v112, v112
	v_rcp_f32_e32 v113, v113
	s_nop 0
	v_pk_mul_f32 v[108:109], v[108:109], v[112:113]
	s_nop 0
	v_pk_mul_f32 v[108:109], v[110:111], v[108:109]
	v_pk_mul_f32 v[110:111], v[98:99], s[24:25] op_sel_hi:[1,0]
	s_nop 0
	v_exp_f32_e32 v110, v110
	v_exp_f32_e32 v111, v111
	s_nop 0
	v_pk_add_f32 v[110:111], v[110:111], 1.0 op_sel_hi:[1,0]
	s_nop 0
	v_rcp_f32_e32 v110, v110
	v_rcp_f32_e32 v111, v111
	s_nop 0
	v_pk_mul_f32 v[98:99], v[98:99], v[110:111]
	s_nop 0
	v_pk_mul_f32 v[110:111], v[102:103], v[98:99]
	v_pk_mul_f32 v[98:99], v[100:101], v[114:115] op_sel_hi:[1,0]
	v_pk_mul_f32 v[100:101], v[104:105], v[114:115] op_sel_hi:[1,0]
	v_pk_mul_f32 v[102:103], v[98:99], s[24:25] op_sel_hi:[1,0]
	s_nop 0
	v_exp_f32_e32 v102, v102
	v_exp_f32_e32 v103, v103
	s_nop 0
	v_pk_add_f32 v[102:103], v[102:103], 1.0 op_sel_hi:[1,0]
	s_nop 0
	v_rcp_f32_e32 v102, v102
	v_rcp_f32_e32 v103, v103
	s_nop 0
	v_pk_mul_f32 v[98:99], v[98:99], v[102:103]
	s_nop 0
	v_pk_mul_f32 v[104:105], v[100:101], v[98:99]
	s_nop 0
	s_nop 0
	s_nop 0
	s_nop 0
	s_nop 0
	v_cvt_pk_bf16_f32 v101, v104, v105
	v_cndmask_b32_e64 v104, 0, 1, s[52:53]
	v_cvt_pk_bf16_f32 v98, v106, v107
	v_cvt_pk_bf16_f32 v99, v108, v109
	v_cvt_pk_bf16_f32 v100, v110, v111
	v_cmp_ne_u32_e64 s[6:7], 1, v104
	s_cbranch_vccnz .LBB0_267
	s_mov_b64 s[54:55], 0
	global_store_dwordx4 v[186:187], v[98:101], off offset:-2048

.LBB0_269:
	s_waitcnt lgkmcnt(5)
	v_add_f32_e32 v98, v157, v158
	v_fmamk_f32 v98, v98, 0x3a800000, v144
	v_rsq_f32_e32 v98, v98
	s_mov_b64 s[52:53], -1
	s_and_b64 vcc, exec, s[6:7]
	v_mov_b32_e32 v246, v98
	v_pk_mul_f32 v[90:91], v[90:91], v[98:99] op_sel_hi:[1,0]
	v_pk_mul_f32 v[94:95], v[94:95], v[98:99] op_sel_hi:[1,0]
	v_pk_mul_f32 v[100:101], v[90:91], s[24:25] op_sel_hi:[1,0]
	v_pk_mul_f32 v[92:93], v[92:93], v[98:99] op_sel_hi:[1,0]
	v_exp_f32_e32 v100, v100
	v_exp_f32_e32 v101, v101
	v_pk_mul_f32 v[82:83], v[82:83], v[98:99] op_sel_hi:[1,0]
	v_pk_mul_f32 v[86:87], v[86:87], v[98:99] op_sel_hi:[1,0]
	v_pk_add_f32 v[100:101], v[100:101], 1.0 op_sel_hi:[1,0]
	s_nop 0
	v_rcp_f32_e32 v100, v100
	v_rcp_f32_e32 v101, v101
	s_nop 0
	v_pk_mul_f32 v[90:91], v[90:91], v[100:101]
	s_nop 0
	v_pk_mul_f32 v[90:91], v[94:95], v[90:91]
	v_pk_mul_f32 v[94:95], v[96:97], v[98:99] op_sel_hi:[1,0]
	v_pk_mul_f32 v[96:97], v[92:93], s[24:25] op_sel_hi:[1,0]
	s_nop 0
	v_exp_f32_e32 v96, v96
	v_exp_f32_e32 v97, v97
	s_nop 0
	v_pk_add_f32 v[96:97], v[96:97], 1.0 op_sel_hi:[1,0]
	s_nop 0
	v_rcp_f32_e32 v96, v96
	v_rcp_f32_e32 v97, v97
	s_nop 0
	v_pk_mul_f32 v[92:93], v[92:93], v[96:97]
	s_nop 0
	v_pk_mul_f32 v[92:93], v[94:95], v[92:93]
	v_pk_mul_f32 v[94:95], v[82:83], s[24:25] op_sel_hi:[1,0]
	s_nop 0
	v_exp_f32_e32 v94, v94
	v_exp_f32_e32 v95, v95
	s_nop 0
	v_pk_add_f32 v[94:95], v[94:95], 1.0 op_sel_hi:[1,0]
	s_nop 0
	v_rcp_f32_e32 v94, v94
	v_rcp_f32_e32 v95, v95
	s_nop 0
	v_pk_mul_f32 v[82:83], v[82:83], v[94:95]
	s_nop 0
	v_pk_mul_f32 v[94:95], v[86:87], v[82:83]
	v_pk_mul_f32 v[82:83], v[84:85], v[98:99] op_sel_hi:[1,0]
	v_pk_mul_f32 v[84:85], v[88:89], v[98:99] op_sel_hi:[1,0]
	v_pk_mul_f32 v[86:87], v[82:83], s[24:25] op_sel_hi:[1,0]
	s_nop 0
	v_exp_f32_e32 v86, v86
	v_exp_f32_e32 v87, v87
	s_nop 0
	v_pk_add_f32 v[86:87], v[86:87], 1.0 op_sel_hi:[1,0]
	s_nop 0
	v_rcp_f32_e32 v86, v86
	v_rcp_f32_e32 v87, v87
	s_nop 0
	v_pk_mul_f32 v[82:83], v[82:83], v[86:87]
	s_nop 0
	v_pk_mul_f32 v[88:89], v[84:85], v[82:83]
	s_nop 0
	v_cvt_pk_bf16_f32 v82, v90, v91
	v_cvt_pk_bf16_f32 v83, v92, v93
	v_cvt_pk_bf16_f32 v84, v94, v95
	v_cvt_pk_bf16_f32 v85, v88, v89
	s_cbranch_vccnz .LBB0_271
	s_mov_b64 s[52:53], 0
	global_store_dwordx4 v[186:187], v[82:85], off

.LBB0_273:
	s_waitcnt lgkmcnt(4)
	v_add_f32_e32 v82, v155, v156
	v_fmamk_f32 v82, v82, 0x3a800000, v144
	v_rsq_f32_e32 v82, v82
	s_mov_b64 s[52:53], -1
	s_and_b64 vcc, exec, s[6:7]
	v_mov_b32_e32 v247, v82
	v_pk_mul_f32 v[74:75], v[74:75], v[82:83] op_sel_hi:[1,0]
	v_pk_mul_f32 v[78:79], v[78:79], v[82:83] op_sel_hi:[1,0]
	v_pk_mul_f32 v[84:85], v[74:75], s[24:25] op_sel_hi:[1,0]
	v_pk_mul_f32 v[76:77], v[76:77], v[82:83] op_sel_hi:[1,0]
	v_exp_f32_e32 v84, v84
	v_exp_f32_e32 v85, v85
	v_pk_mul_f32 v[66:67], v[66:67], v[82:83] op_sel_hi:[1,0]
	v_pk_mul_f32 v[70:71], v[70:71], v[82:83] op_sel_hi:[1,0]
	v_pk_add_f32 v[84:85], v[84:85], 1.0 op_sel_hi:[1,0]
	s_nop 0
	v_rcp_f32_e32 v84, v84
	v_rcp_f32_e32 v85, v85
	s_nop 0
	v_pk_mul_f32 v[74:75], v[74:75], v[84:85]
	s_nop 0
	v_pk_mul_f32 v[74:75], v[78:79], v[74:75]
	v_pk_mul_f32 v[78:79], v[80:81], v[82:83] op_sel_hi:[1,0]
	v_pk_mul_f32 v[80:81], v[76:77], s[24:25] op_sel_hi:[1,0]
	s_nop 0
	v_exp_f32_e32 v80, v80
	v_exp_f32_e32 v81, v81
	s_nop 0
	v_pk_add_f32 v[80:81], v[80:81], 1.0 op_sel_hi:[1,0]
	s_nop 0
	v_rcp_f32_e32 v80, v80
	v_rcp_f32_e32 v81, v81
	s_nop 0
	v_pk_mul_f32 v[76:77], v[76:77], v[80:81]
	s_nop 0
	v_pk_mul_f32 v[76:77], v[78:79], v[76:77]
	v_pk_mul_f32 v[78:79], v[66:67], s[24:25] op_sel_hi:[1,0]
	s_nop 0
	v_exp_f32_e32 v78, v78
	v_exp_f32_e32 v79, v79
	s_nop 0
	v_pk_add_f32 v[78:79], v[78:79], 1.0 op_sel_hi:[1,0]
	s_nop 0
	v_rcp_f32_e32 v78, v78
	v_rcp_f32_e32 v79, v79
	s_nop 0
	v_pk_mul_f32 v[66:67], v[66:67], v[78:79]
	s_nop 0
	v_pk_mul_f32 v[78:79], v[70:71], v[66:67]
	v_pk_mul_f32 v[66:67], v[68:69], v[82:83] op_sel_hi:[1,0]
	v_pk_mul_f32 v[68:69], v[72:73], v[82:83] op_sel_hi:[1,0]
	v_pk_mul_f32 v[70:71], v[66:67], s[24:25] op_sel_hi:[1,0]
	s_nop 0
	v_exp_f32_e32 v70, v70
	v_exp_f32_e32 v71, v71
	s_nop 0
	v_pk_add_f32 v[70:71], v[70:71], 1.0 op_sel_hi:[1,0]
	s_nop 0
	v_rcp_f32_e32 v70, v70
	v_rcp_f32_e32 v71, v71
	s_nop 0
	v_pk_mul_f32 v[66:67], v[66:67], v[70:71]
	s_nop 0
	v_pk_mul_f32 v[72:73], v[68:69], v[66:67]
	s_nop 0
	v_cvt_pk_bf16_f32 v66, v74, v75
	v_cvt_pk_bf16_f32 v67, v76, v77
	v_cvt_pk_bf16_f32 v68, v78, v79
	v_cvt_pk_bf16_f32 v69, v72, v73
	s_cbranch_vccnz .LBB0_275
	s_mov_b64 s[52:53], 0
	global_store_dwordx4 v[186:187], v[66:69], off offset:2048

.LBB0_277:
	s_waitcnt lgkmcnt(3)
	v_add_f32_e32 v66, v153, v154
	v_fmamk_f32 v66, v66, 0x3a800000, v144
	v_rsq_f32_e32 v66, v66
	s_nop 0
	s_mov_b64 s[52:53], -1
	v_mov_b32_e32 v250, v66
	v_pk_mul_f32 v[58:59], v[58:59], v[66:67] op_sel_hi:[1,0]
	v_pk_mul_f32 v[62:63], v[62:63], v[66:67] op_sel_hi:[1,0]
	v_pk_mul_f32 v[68:69], v[58:59], s[24:25] op_sel_hi:[1,0]
	v_pk_mul_f32 v[60:61], v[60:61], v[66:67] op_sel_hi:[1,0]
	v_exp_f32_e32 v68, v68
	v_exp_f32_e32 v69, v69
	v_pk_mul_f32 v[50:51], v[50:51], v[66:67] op_sel_hi:[1,0]
	v_pk_mul_f32 v[54:55], v[54:55], v[66:67] op_sel_hi:[1,0]
	s_and_b64 vcc, exec, s[6:7]
	v_pk_add_f32 v[68:69], v[68:69], 1.0 op_sel_hi:[1,0]
	s_nop 0
	v_rcp_f32_e32 v68, v68
	v_rcp_f32_e32 v69, v69
	s_nop 0
	v_pk_mul_f32 v[58:59], v[58:59], v[68:69]
	s_nop 0
	v_pk_mul_f32 v[58:59], v[62:63], v[58:59]
	v_pk_mul_f32 v[62:63], v[64:65], v[66:67] op_sel_hi:[1,0]
	v_pk_mul_f32 v[64:65], v[60:61], s[24:25] op_sel_hi:[1,0]
	s_nop 0
	v_exp_f32_e32 v64, v64
	v_exp_f32_e32 v65, v65
	s_nop 0
	v_pk_add_f32 v[64:65], v[64:65], 1.0 op_sel_hi:[1,0]
	s_nop 0
	v_rcp_f32_e32 v64, v64
	v_rcp_f32_e32 v65, v65
	s_nop 0
	v_pk_mul_f32 v[60:61], v[60:61], v[64:65]
	s_nop 0
	v_pk_mul_f32 v[60:61], v[62:63], v[60:61]
	v_pk_mul_f32 v[62:63], v[50:51], s[24:25] op_sel_hi:[1,0]
	s_nop 0
	v_exp_f32_e32 v62, v62
	v_exp_f32_e32 v63, v63
	s_nop 0
	v_pk_add_f32 v[62:63], v[62:63], 1.0 op_sel_hi:[1,0]
	s_nop 0
	v_rcp_f32_e32 v62, v62
	v_rcp_f32_e32 v63, v63
	s_nop 0
	v_pk_mul_f32 v[50:51], v[50:51], v[62:63]
	s_nop 0
	v_pk_mul_f32 v[62:63], v[54:55], v[50:51]
	v_pk_mul_f32 v[50:51], v[52:53], v[66:67] op_sel_hi:[1,0]
	v_pk_mul_f32 v[52:53], v[56:57], v[66:67] op_sel_hi:[1,0]
	v_pk_mul_f32 v[54:55], v[50:51], s[24:25] op_sel_hi:[1,0]
	s_nop 0
	v_exp_f32_e32 v54, v54
	v_exp_f32_e32 v55, v55
	s_nop 0
	v_pk_add_f32 v[54:55], v[54:55], 1.0 op_sel_hi:[1,0]
	s_nop 0
	v_rcp_f32_e32 v54, v54
	v_rcp_f32_e32 v55, v55
	s_nop 0
	v_pk_mul_f32 v[50:51], v[50:51], v[54:55]
	s_nop 0
	v_pk_mul_f32 v[56:57], v[52:53], v[50:51]
	s_nop 0
	v_cvt_pk_bf16_f32 v50, v58, v59
	v_cvt_pk_bf16_f32 v51, v60, v61
	v_cvt_pk_bf16_f32 v52, v62, v63
	v_cvt_pk_bf16_f32 v53, v56, v57
	s_mov_b32 s98, 0x5000
	s_mov_b32 s99, 0x0
	v_lshl_add_u64 v[186:187], v[184:185], 0, s[98:99]
	s_cbranch_vccnz .LBB0_279
	s_mov_b64 s[52:53], 0
	global_store_dwordx4 v[186:187], v[50:53], off offset:-4096

.LBB0_281:
	s_waitcnt lgkmcnt(2)
	v_add_f32_e32 v50, v151, v152
	v_fmamk_f32 v50, v50, 0x3a800000, v144
	v_rsq_f32_e32 v50, v50
	s_mov_b64 s[52:53], -1
	s_and_b64 vcc, exec, s[6:7]
	v_mov_b32_e32 v251, v50
	v_pk_mul_f32 v[42:43], v[42:43], v[50:51] op_sel_hi:[1,0]
	v_pk_mul_f32 v[46:47], v[46:47], v[50:51] op_sel_hi:[1,0]
	v_pk_mul_f32 v[52:53], v[42:43], s[24:25] op_sel_hi:[1,0]
	v_pk_mul_f32 v[44:45], v[44:45], v[50:51] op_sel_hi:[1,0]
	v_exp_f32_e32 v52, v52
	v_exp_f32_e32 v53, v53
	v_pk_mul_f32 v[34:35], v[34:35], v[50:51] op_sel_hi:[1,0]
	v_pk_mul_f32 v[38:39], v[38:39], v[50:51] op_sel_hi:[1,0]
	v_pk_add_f32 v[52:53], v[52:53], 1.0 op_sel_hi:[1,0]
	s_nop 0
	v_rcp_f32_e32 v52, v52
	v_rcp_f32_e32 v53, v53
	s_nop 0
	v_pk_mul_f32 v[42:43], v[42:43], v[52:53]
	s_nop 0
	v_pk_mul_f32 v[42:43], v[46:47], v[42:43]
	v_pk_mul_f32 v[46:47], v[48:49], v[50:51] op_sel_hi:[1,0]
	v_pk_mul_f32 v[48:49], v[44:45], s[24:25] op_sel_hi:[1,0]
	s_nop 0
	v_exp_f32_e32 v48, v48
	v_exp_f32_e32 v49, v49
	s_nop 0
	v_pk_add_f32 v[48:49], v[48:49], 1.0 op_sel_hi:[1,0]
	s_nop 0
	v_rcp_f32_e32 v48, v48
	v_rcp_f32_e32 v49, v49
	s_nop 0
	v_pk_mul_f32 v[44:45], v[44:45], v[48:49]
	s_nop 0
	v_pk_mul_f32 v[44:45], v[46:47], v[44:45]
	v_pk_mul_f32 v[46:47], v[34:35], s[24:25] op_sel_hi:[1,0]
	s_nop 0
	v_exp_f32_e32 v46, v46
	v_exp_f32_e32 v47, v47
	s_nop 0
	v_pk_add_f32 v[46:47], v[46:47], 1.0 op_sel_hi:[1,0]
	s_nop 0
	v_rcp_f32_e32 v46, v46
	v_rcp_f32_e32 v47, v47
	s_nop 0
	v_pk_mul_f32 v[34:35], v[34:35], v[46:47]
	s_nop 0
	v_pk_mul_f32 v[46:47], v[38:39], v[34:35]
	v_pk_mul_f32 v[34:35], v[36:37], v[50:51] op_sel_hi:[1,0]
	v_pk_mul_f32 v[36:37], v[40:41], v[50:51] op_sel_hi:[1,0]
	v_pk_mul_f32 v[38:39], v[34:35], s[24:25] op_sel_hi:[1,0]
	s_nop 0
	v_exp_f32_e32 v38, v38
	v_exp_f32_e32 v39, v39
	s_nop 0
	v_pk_add_f32 v[38:39], v[38:39], 1.0 op_sel_hi:[1,0]
	s_nop 0
	v_rcp_f32_e32 v38, v38
	v_rcp_f32_e32 v39, v39
	s_nop 0
	v_pk_mul_f32 v[34:35], v[34:35], v[38:39]
	s_nop 0
	v_pk_mul_f32 v[40:41], v[36:37], v[34:35]
	s_nop 0
	v_cvt_pk_bf16_f32 v34, v42, v43
	v_cvt_pk_bf16_f32 v35, v44, v45
	v_cvt_pk_bf16_f32 v36, v46, v47
	v_cvt_pk_bf16_f32 v37, v40, v41
	s_cbranch_vccnz .LBB0_283
	s_mov_b64 s[52:53], 0
	global_store_dwordx4 v[186:187], v[34:37], off offset:-2048

.LBB0_285:
	s_waitcnt lgkmcnt(1)
	v_add_f32_e32 v34, v149, v150
	v_fmamk_f32 v34, v34, 0x3a800000, v144
	v_rsq_f32_e32 v34, v34
	s_mov_b64 s[52:53], -1
	s_and_b64 vcc, exec, s[6:7]
	v_mov_b32_e32 v252, v34
	v_pk_mul_f32 v[26:27], v[26:27], v[34:35] op_sel_hi:[1,0]
	v_pk_mul_f32 v[30:31], v[30:31], v[34:35] op_sel_hi:[1,0]
	v_pk_mul_f32 v[36:37], v[26:27], s[24:25] op_sel_hi:[1,0]
	v_pk_mul_f32 v[28:29], v[28:29], v[34:35] op_sel_hi:[1,0]
	v_exp_f32_e32 v36, v36
	v_exp_f32_e32 v37, v37
	v_pk_mul_f32 v[18:19], v[18:19], v[34:35] op_sel_hi:[1,0]
	v_pk_mul_f32 v[22:23], v[22:23], v[34:35] op_sel_hi:[1,0]
	v_pk_add_f32 v[36:37], v[36:37], 1.0 op_sel_hi:[1,0]
	s_nop 0
	v_rcp_f32_e32 v36, v36
	v_rcp_f32_e32 v37, v37
	s_nop 0
	v_pk_mul_f32 v[26:27], v[26:27], v[36:37]
	s_nop 0
	v_pk_mul_f32 v[26:27], v[30:31], v[26:27]
	v_pk_mul_f32 v[30:31], v[32:33], v[34:35] op_sel_hi:[1,0]
	v_pk_mul_f32 v[32:33], v[28:29], s[24:25] op_sel_hi:[1,0]
	s_nop 0
	v_exp_f32_e32 v32, v32
	v_exp_f32_e32 v33, v33
	s_nop 0
	v_pk_add_f32 v[32:33], v[32:33], 1.0 op_sel_hi:[1,0]
	s_nop 0
	v_rcp_f32_e32 v32, v32
	v_rcp_f32_e32 v33, v33
	s_nop 0
	v_pk_mul_f32 v[28:29], v[28:29], v[32:33]
	s_nop 0
	v_pk_mul_f32 v[28:29], v[30:31], v[28:29]
	v_pk_mul_f32 v[30:31], v[18:19], s[24:25] op_sel_hi:[1,0]
	s_nop 0
	v_exp_f32_e32 v30, v30
	v_exp_f32_e32 v31, v31
	s_nop 0
	v_pk_add_f32 v[30:31], v[30:31], 1.0 op_sel_hi:[1,0]
	s_nop 0
	v_rcp_f32_e32 v30, v30
	v_rcp_f32_e32 v31, v31
	s_nop 0
	v_pk_mul_f32 v[18:19], v[18:19], v[30:31]
	s_nop 0
	v_pk_mul_f32 v[30:31], v[22:23], v[18:19]
	v_pk_mul_f32 v[18:19], v[20:21], v[34:35] op_sel_hi:[1,0]
	v_pk_mul_f32 v[20:21], v[24:25], v[34:35] op_sel_hi:[1,0]
	v_pk_mul_f32 v[22:23], v[18:19], s[24:25] op_sel_hi:[1,0]
	s_nop 0
	v_exp_f32_e32 v22, v22
	v_exp_f32_e32 v23, v23
	s_nop 0
	v_pk_add_f32 v[22:23], v[22:23], 1.0 op_sel_hi:[1,0]
	s_nop 0
	v_rcp_f32_e32 v22, v22
	v_rcp_f32_e32 v23, v23
	s_nop 0
	v_pk_mul_f32 v[18:19], v[18:19], v[22:23]
	s_nop 0
	v_pk_mul_f32 v[24:25], v[20:21], v[18:19]
	s_nop 0
	v_cvt_pk_bf16_f32 v18, v26, v27
	v_cvt_pk_bf16_f32 v19, v28, v29
	v_cvt_pk_bf16_f32 v20, v30, v31
	v_cvt_pk_bf16_f32 v21, v24, v25
	s_cbranch_vccnz .LBB0_287
	s_mov_b64 s[52:53], 0
	global_store_dwordx4 v[186:187], v[18:21], off

.LBB0_289:
	s_waitcnt lgkmcnt(0)
	v_add_f32_e32 v18, v147, v148
	v_fmamk_f32 v18, v18, 0x3a800000, v144
	v_rsq_f32_e32 v18, v18
	s_and_b64 vcc, exec, s[6:7]
	v_mov_b32_e32 v253, v18
	v_pk_mul_f32 v[10:11], v[10:11], v[18:19] op_sel_hi:[1,0]
	s_nop 0
	v_pk_mul_f32 v[20:21], v[10:11], s[24:25] op_sel_hi:[1,0]
	v_pk_mul_f32 v[14:15], v[14:15], v[18:19] op_sel_hi:[1,0]
	v_exp_f32_e32 v20, v20
	v_exp_f32_e32 v21, v21
	v_pk_mul_f32 v[12:13], v[12:13], v[18:19] op_sel_hi:[1,0]
	v_pk_mul_f32 v[2:3], v[2:3], v[18:19] op_sel_hi:[1,0]
	v_pk_mul_f32 v[6:7], v[6:7], v[18:19] op_sel_hi:[1,0]
	v_pk_add_f32 v[20:21], v[20:21], 1.0 op_sel_hi:[1,0]
	s_nop 0
	v_rcp_f32_e32 v20, v20
	v_rcp_f32_e32 v21, v21
	s_nop 0
	v_pk_mul_f32 v[10:11], v[10:11], v[20:21]
	s_nop 0
	v_pk_mul_f32 v[10:11], v[14:15], v[10:11]
	v_pk_mul_f32 v[14:15], v[16:17], v[18:19] op_sel_hi:[1,0]
	v_pk_mul_f32 v[16:17], v[12:13], s[24:25] op_sel_hi:[1,0]
	s_nop 0
	v_exp_f32_e32 v16, v16
	v_exp_f32_e32 v17, v17
	s_nop 0
	v_pk_add_f32 v[16:17], v[16:17], 1.0 op_sel_hi:[1,0]
	s_nop 0
	v_rcp_f32_e32 v16, v16
	v_rcp_f32_e32 v17, v17
	s_nop 0
	v_pk_mul_f32 v[12:13], v[12:13], v[16:17]
	s_nop 0
	v_pk_mul_f32 v[12:13], v[14:15], v[12:13]
	v_pk_mul_f32 v[14:15], v[2:3], s[24:25] op_sel_hi:[1,0]
	s_nop 0
	v_exp_f32_e32 v14, v14
	v_exp_f32_e32 v15, v15
	s_nop 0
	v_pk_add_f32 v[14:15], v[14:15], 1.0 op_sel_hi:[1,0]
	s_nop 0
	v_rcp_f32_e32 v14, v14
	v_rcp_f32_e32 v15, v15
	s_nop 0
	v_pk_mul_f32 v[2:3], v[2:3], v[14:15]
	s_nop 0
	v_pk_mul_f32 v[14:15], v[6:7], v[2:3]
	v_pk_mul_f32 v[2:3], v[4:5], v[18:19] op_sel_hi:[1,0]
	v_pk_mul_f32 v[4:5], v[8:9], v[18:19] op_sel_hi:[1,0]
	v_pk_mul_f32 v[6:7], v[2:3], s[24:25] op_sel_hi:[1,0]
	s_nop 0
	v_exp_f32_e32 v6, v6
	v_exp_f32_e32 v7, v7
	s_nop 0
	v_pk_add_f32 v[6:7], v[6:7], 1.0 op_sel_hi:[1,0]
	s_nop 0
	v_rcp_f32_e32 v6, v6
	v_rcp_f32_e32 v7, v7
	s_nop 0
	v_pk_mul_f32 v[2:3], v[2:3], v[6:7]
	s_nop 0
	v_pk_mul_f32 v[8:9], v[4:5], v[2:3]
	s_nop 0
	v_cvt_pk_bf16_f32 v2, v10, v11
	v_cvt_pk_bf16_f32 v3, v12, v13
	v_cvt_pk_bf16_f32 v4, v14, v15
	v_cvt_pk_bf16_f32 v5, v8, v9
	s_mov_b64 s[50:51], -1
	s_cbranch_vccnz .LBB0_291
	s_mov_b64 s[50:51], 0
	global_store_dwordx4 v[186:187], v[2:5], off offset:2048

.LBB0_675:
	s_nop 0
	s_nop 0
	s_nop 0
	s_nop 0
	v_pk_fma_f32 v[146:147], v[62:63], v[164:165], v[142:143] op_sel_hi:[1,0,1]
	v_pk_fma_f32 v[148:149], v[64:65], v[164:165], v[144:145] op_sel_hi:[1,0,1]
	v_pk_mul_f32 v[146:147], v[146:147], s[94:95] op_sel_hi:[1,0]
	v_pk_mul_f32 v[148:149], v[148:149], s[94:95] op_sel_hi:[1,0]
	v_exp_f32_e32 v146, v146
	v_exp_f32_e32 v147, v147
	v_exp_f32_e32 v148, v148
	v_exp_f32_e32 v149, v149
	s_and_b64 vcc, exec, s[0:1]
	v_pk_add_f32 v[146:147], v[146:147], 1.0 op_sel_hi:[1,0]
	s_mov_b64 s[22:23], -1
	v_rcp_f32_e32 v165, v147
	v_rcp_f32_e32 v157, v146
	v_pk_add_f32 v[146:147], v[148:149], 1.0 op_sel_hi:[1,0]
	v_pk_fma_f32 v[148:149], v[60:61], v[164:165], v[140:141] op_sel_hi:[1,0,1]
	v_rcp_f32_e32 v169, v146
	v_rcp_f32_e32 v173, v147
	v_pk_fma_f32 v[146:147], v[58:59], v[164:165], v[138:139] op_sel_hi:[1,0,1]
	v_pk_mul_f32 v[148:149], v[148:149], s[94:95] op_sel_hi:[1,0]
	v_pk_mul_f32 v[146:147], v[146:147], s[94:95] op_sel_hi:[1,0]
	v_exp_f32_e32 v148, v148
	v_exp_f32_e32 v146, v146
	v_exp_f32_e32 v147, v147
	v_exp_f32_e32 v149, v149
	v_pk_add_f32 v[146:147], v[146:147], 1.0 op_sel_hi:[1,0]
	s_nop 0
	v_rcp_f32_e32 v177, v146
	v_rcp_f32_e32 v225, v147
	v_pk_add_f32 v[146:147], v[148:149], 1.0 op_sel_hi:[1,0]
	v_cvt_pk_bf16_f32 v148, v177, v225
	v_rcp_f32_e32 v149, v146
	v_rcp_f32_e32 v226, v147
	s_nop 0
	s_nop 0
	s_nop 0
	s_nop 0
	s_nop 0
	v_cvt_pk_bf16_f32 v146, v157, v165
	v_cvt_pk_bf16_f32 v147, v169, v173
	v_cvt_pk_bf16_f32 v149, v149, v226
	s_mov_b32 s98, 0x5000
	s_mov_b32 s99, 0x0
	v_lshl_add_u64 v[252:253], v[250:251], 0, s[98:99]
	s_cbranch_vccnz .LBB0_677
	s_mov_b64 s[22:23], 0
	global_store_dwordx4 v[252:253], v[146:149], off offset:-4096

.LBB0_683:
	s_nop 0
	s_nop 0
	s_nop 0
	s_nop 0
	v_pk_fma_f32 v[146:147], v[54:55], v[160:161], v[142:143] op_sel_hi:[1,0,1]
	v_pk_fma_f32 v[148:149], v[56:57], v[160:161], v[144:145] op_sel_hi:[1,0,1]
	v_pk_mul_f32 v[146:147], v[146:147], s[94:95] op_sel_hi:[1,0]
	v_pk_mul_f32 v[148:149], v[148:149], s[94:95] op_sel_hi:[1,0]
	v_exp_f32_e32 v146, v146
	v_exp_f32_e32 v147, v147
	v_exp_f32_e32 v148, v148
	v_exp_f32_e32 v149, v149
	s_and_b64 vcc, exec, s[0:1]
	v_pk_add_f32 v[146:147], v[146:147], 1.0 op_sel_hi:[1,0]
	s_mov_b64 s[22:23], -1
	v_rcp_f32_e32 v161, v146
	v_rcp_f32_e32 v165, v147
	v_pk_add_f32 v[146:147], v[148:149], 1.0 op_sel_hi:[1,0]
	v_pk_fma_f32 v[148:149], v[52:53], v[160:161], v[140:141] op_sel_hi:[1,0,1]
	v_rcp_f32_e32 v169, v146
	v_rcp_f32_e32 v173, v147
	v_pk_fma_f32 v[146:147], v[50:51], v[160:161], v[138:139] op_sel_hi:[1,0,1]
	v_pk_mul_f32 v[148:149], v[148:149], s[94:95] op_sel_hi:[1,0]
	v_pk_mul_f32 v[146:147], v[146:147], s[94:95] op_sel_hi:[1,0]
	v_exp_f32_e32 v148, v148
	v_exp_f32_e32 v146, v146
	v_exp_f32_e32 v147, v147
	v_exp_f32_e32 v149, v149
	v_pk_add_f32 v[146:147], v[146:147], 1.0 op_sel_hi:[1,0]
	s_nop 0
	v_rcp_f32_e32 v177, v146
	v_rcp_f32_e32 v225, v147
	v_pk_add_f32 v[146:147], v[148:149], 1.0 op_sel_hi:[1,0]
	v_cvt_pk_bf16_f32 v148, v177, v225
	v_rcp_f32_e32 v149, v146
	v_rcp_f32_e32 v226, v147
	s_nop 0
	s_nop 0
	s_nop 0
	s_nop 0
	s_nop 0
	v_cvt_pk_bf16_f32 v146, v161, v165
	v_cvt_pk_bf16_f32 v147, v169, v173
	v_cvt_pk_bf16_f32 v149, v149, v226
	s_cbranch_vccnz .LBB0_685
	s_mov_b64 s[22:23], 0
	global_store_dwordx4 v[252:253], v[146:149], off offset:-2048

.LBB0_1106:
	s_nop 0
	s_nop 0
	s_nop 0
	s_nop 0
	v_pk_fma_f32 v[146:147], v[62:63], v[168:169], v[142:143] op_sel_hi:[1,0,1]
	v_pk_fma_f32 v[148:149], v[64:65], v[168:169], v[144:145] op_sel_hi:[1,0,1]
	v_pk_mul_f32 v[146:147], v[146:147], s[38:39] op_sel_hi:[1,0]
	v_pk_mul_f32 v[148:149], v[148:149], s[38:39] op_sel_hi:[1,0]
	v_exp_f32_e32 v146, v146
	v_exp_f32_e32 v147, v147
	v_exp_f32_e32 v148, v148
	v_exp_f32_e32 v149, v149
	s_and_b64 vcc, exec, s[0:1]
	v_pk_add_f32 v[146:147], v[146:147], 1.0 op_sel_hi:[1,0]
	s_mov_b64 s[62:63], -1
	v_rcp_f32_e32 v169, v147
	v_rcp_f32_e32 v161, v146
	v_pk_add_f32 v[146:147], v[148:149], 1.0 op_sel_hi:[1,0]
	v_pk_fma_f32 v[148:149], v[60:61], v[168:169], v[140:141] op_sel_hi:[1,0,1]
	v_rcp_f32_e32 v173, v146
	v_rcp_f32_e32 v177, v147
	v_pk_fma_f32 v[146:147], v[58:59], v[168:169], v[138:139] op_sel_hi:[1,0,1]
	v_pk_mul_f32 v[148:149], v[148:149], s[38:39] op_sel_hi:[1,0]
	v_pk_mul_f32 v[146:147], v[146:147], s[38:39] op_sel_hi:[1,0]
	v_exp_f32_e32 v148, v148
	v_exp_f32_e32 v146, v146
	v_exp_f32_e32 v147, v147
	v_exp_f32_e32 v149, v149
	v_pk_add_f32 v[146:147], v[146:147], 1.0 op_sel_hi:[1,0]
	s_nop 0
	v_rcp_f32_e32 v181, v146
	v_rcp_f32_e32 v227, v147
	v_pk_add_f32 v[146:147], v[148:149], 1.0 op_sel_hi:[1,0]
	v_cvt_pk_bf16_f32 v148, v181, v227
	v_rcp_f32_e32 v149, v146
	v_rcp_f32_e32 v228, v147
	s_nop 0
	s_nop 0
	s_nop 0
	s_nop 0
	s_nop 0
	v_cvt_pk_bf16_f32 v146, v161, v169
	v_cvt_pk_bf16_f32 v147, v173, v177
	v_cvt_pk_bf16_f32 v149, v149, v228
	s_mov_b32 s98, 0x5000
	s_mov_b32 s99, 0x0
	v_lshl_add_u64 v[252:253], v[250:251], 0, s[98:99]
	s_cbranch_vccnz .LBB0_1108
	s_mov_b64 s[62:63], 0
	global_store_dwordx4 v[252:253], v[146:149], off offset:-4096

.LBB0_1114:
	s_nop 0
	s_nop 0
	s_nop 0
	s_nop 0
	v_pk_fma_f32 v[146:147], v[46:47], v[164:165], v[142:143] op_sel_hi:[1,0,1]
	v_pk_fma_f32 v[148:149], v[48:49], v[164:165], v[144:145] op_sel_hi:[1,0,1]
	v_pk_mul_f32 v[146:147], v[146:147], s[38:39] op_sel_hi:[1,0]
	v_pk_mul_f32 v[148:149], v[148:149], s[38:39] op_sel_hi:[1,0]
	v_exp_f32_e32 v146, v146
	v_exp_f32_e32 v147, v147
	v_exp_f32_e32 v148, v148
	v_exp_f32_e32 v149, v149
	s_and_b64 vcc, exec, s[0:1]
	v_pk_add_f32 v[146:147], v[146:147], 1.0 op_sel_hi:[1,0]
	s_mov_b64 s[62:63], -1
	v_rcp_f32_e32 v165, v146
	v_rcp_f32_e32 v169, v147
	v_pk_add_f32 v[146:147], v[148:149], 1.0 op_sel_hi:[1,0]
	v_pk_fma_f32 v[148:149], v[44:45], v[164:165], v[140:141] op_sel_hi:[1,0,1]
	v_rcp_f32_e32 v173, v146
	v_rcp_f32_e32 v177, v147
	v_pk_fma_f32 v[146:147], v[42:43], v[164:165], v[138:139] op_sel_hi:[1,0,1]
	v_pk_mul_f32 v[148:149], v[148:149], s[38:39] op_sel_hi:[1,0]
	v_pk_mul_f32 v[146:147], v[146:147], s[38:39] op_sel_hi:[1,0]
	v_exp_f32_e32 v148, v148
	v_exp_f32_e32 v146, v146
	v_exp_f32_e32 v147, v147
	v_exp_f32_e32 v149, v149
	v_pk_add_f32 v[146:147], v[146:147], 1.0 op_sel_hi:[1,0]
	s_nop 0
	v_rcp_f32_e32 v181, v146
	v_rcp_f32_e32 v227, v147
	v_pk_add_f32 v[146:147], v[148:149], 1.0 op_sel_hi:[1,0]
	v_cvt_pk_bf16_f32 v148, v181, v227
	v_rcp_f32_e32 v149, v146
	v_rcp_f32_e32 v228, v147
	s_nop 0
	s_nop 0
	s_nop 0
	s_nop 0
	s_nop 0
	v_cvt_pk_bf16_f32 v146, v165, v169
	v_cvt_pk_bf16_f32 v147, v173, v177
	v_cvt_pk_bf16_f32 v149, v149, v228
	s_cbranch_vccnz .LBB0_1116
	s_mov_b64 s[62:63], 0
	global_store_dwordx4 v[252:253], v[146:149], off offset:-2048

.LBB0_2080:
	s_add_u32 s20, s86, 0x43000
	s_addc_u32 s21, s87, 0
	s_add_u32 s65, s86, 0xac68000
	v_and_b32_e32 v202, 15, v0
	v_and_b32_e32 v2, 48, v0
	v_lshlrev_b32_e32 v4, 2, v0
	s_addc_u32 s66, s87, 0
	s_and_b32 s1, s26, 3
	s_lshl_b32 s68, s0, 6
	s_lshl_b32 s0, s0, 13
	s_waitcnt lgkmcnt(0)
	v_lshl_or_b32 v3, v202, 6, v2
	v_and_b32_e32 v4, 32, v4
	v_lshlrev_b32_e32 v5, 6, v0
	s_movk_i32 s69, 0x3c0
	v_bitop3_b32 v3, v3, s0, v4 bitop3:0xde
	s_lshl_b32 s10, s26, 5
	s_lshl_b32 s0, s1, 12
	v_and_or_b32 v2, v5, s69, v2
	v_bitop3_b32 v2, s0, v2, v4 bitop3:0xf6
	s_add_u32 s0, s18, 0x8000
	s_waitcnt vmcnt(2)
	s_barrier
	s_addc_u32 s1, s19, 0
	s_add_i32 s70, s61, 0x18000
	s_mov_b32 m0, s70
	s_nop 0
	global_load_lds_dwordx4 v195, s[0:1]
	s_add_u32 m0, s70, 0x2000
	s_nop 0
	global_load_lds_dwordx4 v197, s[0:1]
	s_add_u32 s0, s16, 0x8000
	s_addc_u32 s1, s17, 0
	s_add_i32 s71, s61, 0x8000
	s_mov_b32 m0, s71
	s_nop 0
	global_load_lds_dwordx4 v195, s[0:1]
	s_add_u32 m0, s71, 0x2000
	s_nop 0
	global_load_lds_dwordx4 v197, s[0:1]
	s_add_u32 s0, s18, 0xc000
	s_addc_u32 s1, s19, 0
	s_add_i32 s72, s61, 0x1c000
	s_mov_b32 m0, s72
	s_nop 0
	global_load_lds_dwordx4 v195, s[0:1]
	s_add_u32 m0, s72, 0x2000
	s_nop 0
	global_load_lds_dwordx4 v197, s[0:1]
	s_add_i32 s73, s61, 0xc000
	s_cmpk_lt_u32 s24, 0x100
	s_cselect_b64 s[24:25], -1, 0
	s_bfe_u32 s74, s26, 0x10001
	s_and_b32 s75, s10, 32
	s_ashr_i32 s76, s31, 31
	s_and_b32 s10, s31, 7
	s_ashr_i32 s77, s31, 3
	s_cmp_eq_u32 s77, 6
	s_cselect_b64 s[26:27], -1, 0
	s_sub_i32 s11, s77, 17
	s_waitcnt vmcnt(6)
	s_cmp_lt_u32 s11, 2
	s_cselect_b64 s[28:29], -1, 0
	s_lshl_b32 s78, s77, 5
	s_and_b32 s80, s31, 1
	v_mov_b32_e32 v199, 0
	v_cmp_ne_u32_e64 s[0:1], 0, v196
	v_cmp_gt_u32_e64 s[6:7], 64, v0
	s_addk_i32 s78, 0xff06
	s_or_b32 s79, s10, 0xfffff500
	s_bitset1_b32 s80, 7
	s_lshl_b32 s81, s10, 4
	s_mov_b32 s15, -1
	v_mov_b32_e32 v203, 1
	v_mbcnt_hi_u32_b32 v204, -1, v211
	v_mov_b32_e32 v205, 0x358637bd
	s_mov_b32 s30, 0xbfb8aa3b
	v_mov_b64_e32 v[200:201], 0xb2b
	v_add_u32_e32 v206, 0, v2
	v_add_u32_e32 v207, 0, v3
	s_mov_b32 s10, s14
	v_mov_b32_e32 v2, v199
	v_mov_b32_e32 v3, v199
	v_mov_b32_e32 v4, v199
	v_mov_b32_e32 v5, v199
	v_mov_b32_e32 v6, v199
	v_mov_b32_e32 v7, v199
	v_mov_b32_e32 v8, v199
	v_mov_b32_e32 v9, v199
	v_mov_b32_e32 v10, v199
	v_mov_b32_e32 v11, v199
	v_mov_b32_e32 v12, v199
	v_mov_b32_e32 v13, v199
	v_mov_b32_e32 v14, v199
	v_mov_b32_e32 v15, v199
	v_mov_b32_e32 v16, v199
	v_mov_b32_e32 v17, v199
	v_mov_b32_e32 v18, v199
	v_mov_b32_e32 v19, v199
	v_mov_b32_e32 v20, v199
	v_mov_b32_e32 v21, v199
	v_mov_b32_e32 v22, v199
	v_mov_b32_e32 v23, v199
	v_mov_b32_e32 v24, v199
	v_mov_b32_e32 v25, v199
	v_mov_b32_e32 v26, v199
	v_mov_b32_e32 v27, v199
	v_mov_b32_e32 v28, v199
	v_mov_b32_e32 v29, v199
	v_mov_b32_e32 v30, v199
	v_mov_b32_e32 v31, v199
	v_mov_b32_e32 v32, v199
	v_mov_b32_e32 v33, v199
	v_mov_b32_e32 v34, v199
	v_mov_b32_e32 v35, v199
	v_mov_b32_e32 v36, v199
	v_mov_b32_e32 v37, v199
	v_mov_b32_e32 v38, v199
	v_mov_b32_e32 v39, v199
	v_mov_b32_e32 v40, v199
	v_mov_b32_e32 v41, v199
	v_mov_b32_e32 v42, v199
	v_mov_b32_e32 v43, v199
	v_mov_b32_e32 v44, v199
	v_mov_b32_e32 v45, v199
	v_mov_b32_e32 v46, v199
	v_mov_b32_e32 v47, v199
	v_mov_b32_e32 v48, v199
	v_mov_b32_e32 v49, v199
	v_mov_b32_e32 v50, v199
	v_mov_b32_e32 v51, v199
	v_mov_b32_e32 v52, v199
	v_mov_b32_e32 v53, v199
	v_mov_b32_e32 v54, v199
	v_mov_b32_e32 v55, v199
	v_mov_b32_e32 v56, v199
	v_mov_b32_e32 v57, v199
	v_mov_b32_e32 v58, v199
	v_mov_b32_e32 v59, v199
	v_mov_b32_e32 v60, v199
	v_mov_b32_e32 v61, v199
	v_mov_b32_e32 v62, v199
	v_mov_b32_e32 v63, v199
	v_mov_b32_e32 v64, v199
	v_mov_b32_e32 v65, v199
	v_mov_b32_e32 v66, v199
	v_mov_b32_e32 v67, v199
	v_mov_b32_e32 v68, v199
	v_mov_b32_e32 v69, v199
	v_mov_b32_e32 v70, v199
	v_mov_b32_e32 v71, v199
	v_mov_b32_e32 v72, v199
	v_mov_b32_e32 v73, v199
	v_mov_b32_e32 v74, v199
	v_mov_b32_e32 v75, v199
	v_mov_b32_e32 v76, v199
	v_mov_b32_e32 v77, v199
	v_mov_b32_e32 v78, v199
	v_mov_b32_e32 v79, v199
	v_mov_b32_e32 v80, v199
	v_mov_b32_e32 v81, v199
	v_mov_b32_e32 v82, v199
	v_mov_b32_e32 v83, v199
	v_mov_b32_e32 v84, v199
	v_mov_b32_e32 v85, v199
	v_mov_b32_e32 v86, v199
	v_mov_b32_e32 v87, v199
	v_mov_b32_e32 v88, v199
	v_mov_b32_e32 v89, v199
	v_mov_b32_e32 v90, v199
	v_mov_b32_e32 v91, v199
	v_mov_b32_e32 v92, v199
	v_mov_b32_e32 v93, v199
	v_mov_b32_e32 v94, v199
	v_mov_b32_e32 v95, v199
	v_mov_b32_e32 v96, v199
	v_mov_b32_e32 v97, v199
	v_mov_b32_e32 v98, v199
	v_mov_b32_e32 v99, v199
	v_mov_b32_e32 v100, v199
	v_mov_b32_e32 v101, v199
	v_mov_b32_e32 v102, v199
	v_mov_b32_e32 v103, v199
	v_mov_b32_e32 v104, v199
	v_mov_b32_e32 v105, v199
	v_mov_b32_e32 v106, v199
	v_mov_b32_e32 v107, v199
	v_mov_b32_e32 v108, v199
	v_mov_b32_e32 v109, v199
	v_mov_b32_e32 v110, v199
	v_mov_b32_e32 v111, v199
	v_mov_b32_e32 v112, v199
	v_mov_b32_e32 v113, v199
	v_mov_b32_e32 v114, v199
	v_mov_b32_e32 v115, v199
	v_mov_b32_e32 v116, v199
	v_mov_b32_e32 v117, v199
	v_mov_b32_e32 v118, v199
	v_mov_b32_e32 v119, v199
	v_mov_b32_e32 v120, v199
	v_mov_b32_e32 v121, v199
	v_mov_b32_e32 v122, v199
	v_mov_b32_e32 v123, v199
	v_mov_b32_e32 v124, v199
	v_mov_b32_e32 v125, v199
	v_mov_b32_e32 v126, v199
	v_mov_b32_e32 v127, v199
	v_mov_b32_e32 v128, v199
	v_mov_b32_e32 v129, v199
	s_barrier
	s_mov_b32 s100, -1

.LBB0_2124:
	s_cmp_eq_u32 s82, s100
	s_cbranch_scc0 .Lcr1_slow
	s_and_b64 vcc, exec, s[24:25]
	s_cbranch_vccz .Lcr1_2126
	s_barrier
.Lcr1_2126:
	v_mov_b32_e32 v137, v210
	v_mov_b32_e32 v130, v202
	v_xor_b32_e32 v138, 32, v204
	v_add_u32_e32 v136, s68, v130
	v_lshl_add_u32 v130, s82, 8, v136
	v_lshlrev_b32_e32 v132, 2, v137
	v_ashrrev_i32_e32 v133, 31, v132
	v_ashrrev_i32_e32 v131, 31, v130
	v_lshl_add_u64 v[132:133], v[132:133], 2, s[2:3]
	v_lshlrev_b64 v[130:131], 6, v[130:131]
	v_lshl_add_u64 v[134:135], v[132:133], 0, v[130:131]
	s_mov_b32 s98, 0x1000
	s_mov_b32 s99, 0x0
	v_add_co_u32_e32 v134, vcc, s13, v134
	s_mul_i32 s10, s82, 44
	s_nop 0
	v_addc_co_u32_e32 v135, vcc, 0, v135, vcc
	v_and_b32_e32 v135, 64, v204
	v_xor_b32_e32 v134, 16, v204
	v_add_u32_e32 v135, 64, v135
	v_cmp_lt_i32_e32 vcc, v134, v135
	s_lshl_b32 s11, s12, 1
	s_add_i32 s10, s10, s11
	v_cndmask_b32_e32 v134, v204, v134, vcc
	v_cmp_lt_i32_e32 vcc, v138, v135
	v_lshlrev_b32_e32 v139, 2, v134
	s_or_b32 s10, s10, s74
	s_nop 0
	s_nop 0
	s_ashr_i32 s11, s10, 31
	v_lshl_add_u32 v138, v137, 3, s75
	s_lshl_b64 s[10:11], s[10:11], 15
	v_lshlrev_b32_e32 v137, 4, v137
	v_ashrrev_i32_e32 v138, 5, v138
	s_add_u32 s50, s65, s10
	v_and_b32_e32 v137, 48, v137
	s_addc_u32 s51, s66, s11
	s_cmpk_lt_i32 s82, 0x80
	s_cselect_b64 s[52:53], -1, 0
	s_xor_b64 s[54:55], s[36:37], -1
	s_and_b64 s[52:53], s[54:55], s[52:53]
	s_mov_b64 s[10:11], -1
	s_and_b64 vcc, exec, s[52:53]
	v_add_f32_e32 v135, v152, v153
	v_add_f32_e32 v140, v154, v155
	v_add_f32_e32 v135, v135, v140
	ds_bpermute_b32 v144, v139, v135
	s_waitcnt lgkmcnt(4)
	s_waitcnt lgkmcnt(3)
	s_waitcnt lgkmcnt(1)
	v_mov_b32_e32 v130, v244
	v_add_f32_e32 v145, v135, v144
	v_pk_mul_f32 v[134:135], v[128:129], v[130:131] op_sel_hi:[1,0]
	v_pk_mul_f32 v[132:133], v[126:127], v[130:131] op_sel_hi:[1,0]
	v_pk_mul_f32 v[156:157], v[134:135], s[30:31] op_sel_hi:[1,0]
	s_waitcnt lgkmcnt(0)
	v_pk_mul_f32 v[154:155], v[132:133], s[30:31] op_sel_hi:[1,0]
	v_exp_f32_e32 v156, v156
	v_exp_f32_e32 v157, v157
	v_exp_f32_e32 v154, v154
	v_exp_f32_e32 v155, v155
	v_pk_mul_f32 v[160:161], v[96:97], v[130:131] op_sel_hi:[1,0]
	v_pk_add_f32 v[156:157], v[156:157], 1.0 op_sel_hi:[1,0]
	v_pk_mul_f32 v[162:163], v[122:123], v[130:131] op_sel_hi:[1,0]
	v_pk_add_f32 v[154:155], v[154:155], 1.0 op_sel_hi:[1,0]
	v_rcp_f32_e32 v156, v156
	v_rcp_f32_e32 v157, v157
	v_rcp_f32_e32 v154, v154
	v_rcp_f32_e32 v155, v155
	v_pk_mul_f32 v[158:159], v[94:95], v[130:131] op_sel_hi:[1,0]
	v_pk_mul_f32 v[134:135], v[134:135], v[156:157]
	v_pk_mul_f32 v[156:157], v[124:125], v[130:131] op_sel_hi:[1,0]
	v_pk_mul_f32 v[132:133], v[132:133], v[154:155]
	v_pk_mul_f32 v[154:155], v[160:161], v[134:135]
	v_pk_mul_f32 v[134:135], v[162:163], s[30:31] op_sel_hi:[1,0]
	v_pk_mul_f32 v[132:133], v[158:159], v[132:133]
	v_exp_f32_e32 v134, v134
	v_exp_f32_e32 v135, v135
	v_pk_mul_f32 v[158:159], v[156:157], s[30:31] op_sel_hi:[1,0]
	s_nop 0
	v_exp_f32_e32 v158, v158
	v_exp_f32_e32 v159, v159
	v_pk_add_f32 v[134:135], v[134:135], 1.0 op_sel_hi:[1,0]
	s_nop 0
	v_rcp_f32_e32 v134, v134
	v_rcp_f32_e32 v135, v135
	v_pk_add_f32 v[158:159], v[158:159], 1.0 op_sel_hi:[1,0]
	v_pk_mul_f32 v[164:165], v[90:91], v[130:131] op_sel_hi:[1,0]
	v_rcp_f32_e32 v158, v158
	v_rcp_f32_e32 v159, v159
	v_pk_mul_f32 v[134:135], v[162:163], v[134:135]
	v_pk_mul_f32 v[130:131], v[92:93], v[130:131] op_sel_hi:[1,0]
	v_pk_mul_f32 v[160:161], v[164:165], v[134:135]
	v_pk_mul_f32 v[134:135], v[156:157], v[158:159]
	s_waitcnt lgkmcnt(1)
	v_pk_mul_f32 v[156:157], v[130:131], v[134:135]
	v_lshrrev_b32_e32 v131, 3, v136
	s_waitcnt lgkmcnt(0)
	v_lshlrev_b32_e32 v130, 7, v136
	v_and_b32_e32 v131, 14, v131
	v_and_b32_e32 v130, 0xffffc000, v130
	v_lshlrev_b32_e32 v134, 6, v136
	v_add_lshl_u32 v147, v131, v138, 10
	v_lshlrev_b32_e32 v131, 2, v136
	v_and_or_b32 v134, v134, s69, v137
	v_and_b32_e32 v131, 32, v131
	v_add_u32_e32 v130, v147, v130
	v_bitop3_b32 v130, v130, v134, v131 bitop3:0xf6
	v_ashrrev_i32_e32 v131, 31, v130
	v_lshl_add_u64 v[134:135], s[50:51], 0, v[130:131]
	v_cvt_pk_bf16_f32 v130, v132, v133
	v_cvt_pk_bf16_f32 v131, v154, v155
	v_cvt_pk_bf16_f32 v132, v160, v161
	v_cvt_pk_bf16_f32 v133, v156, v157
	v_lshl_add_u64 v[170:171], v[134:135], 0, 0
	s_cbranch_vccz .Lcr1_2128
	global_store_dwordx4 v[134:135], v[130:133], off
	s_mov_b64 s[10:11], 0

.Lcr1_2130:
	s_waitcnt lgkmcnt(6)
	s_nop 0
	s_nop 0
	v_mov_b32_e32 v130, v245
	s_andn2_b64 vcc, exec, s[52:53]
	v_pk_mul_f32 v[132:133], v[118:119], v[130:131] op_sel_hi:[1,0]
	s_nop 0
	v_pk_mul_f32 v[152:153], v[132:133], s[30:31] op_sel_hi:[1,0]
	v_pk_mul_f32 v[154:155], v[120:121], v[130:131] op_sel_hi:[1,0]
	v_exp_f32_e32 v152, v152
	v_exp_f32_e32 v153, v153
	v_pk_mul_f32 v[156:157], v[154:155], s[30:31] op_sel_hi:[1,0]
	v_pk_mul_f32 v[134:135], v[86:87], v[130:131] op_sel_hi:[1,0]
	v_exp_f32_e32 v156, v156
	v_exp_f32_e32 v157, v157
	v_pk_add_f32 v[152:153], v[152:153], 1.0 op_sel_hi:[1,0]
	v_pk_mul_f32 v[158:159], v[116:117], v[130:131] op_sel_hi:[1,0]
	v_rcp_f32_e32 v152, v152
	v_rcp_f32_e32 v153, v153
	v_pk_add_f32 v[156:157], v[156:157], 1.0 op_sel_hi:[1,0]
	v_pk_mul_f32 v[160:161], v[158:159], s[30:31] op_sel_hi:[1,0]
	v_rcp_f32_e32 v156, v156
	v_rcp_f32_e32 v157, v157
	v_pk_mul_f32 v[132:133], v[132:133], v[152:153]
	v_exp_f32_e32 v160, v160
	v_pk_mul_f32 v[132:133], v[134:135], v[132:133]
	v_pk_mul_f32 v[134:135], v[88:89], v[130:131] op_sel_hi:[1,0]
	v_pk_mul_f32 v[152:153], v[154:155], v[156:157]
	v_exp_f32_e32 v161, v161
	v_pk_mul_f32 v[152:153], v[134:135], v[152:153]
	v_pk_mul_f32 v[134:135], v[114:115], v[130:131] op_sel_hi:[1,0]
	v_pk_mul_f32 v[154:155], v[82:83], v[130:131] op_sel_hi:[1,0]
	v_pk_mul_f32 v[156:157], v[134:135], s[30:31] op_sel_hi:[1,0]
	v_pk_add_f32 v[160:161], v[160:161], 1.0 op_sel_hi:[1,0]
	v_exp_f32_e32 v156, v156
	v_exp_f32_e32 v157, v157
	v_rcp_f32_e32 v160, v160
	v_rcp_f32_e32 v161, v161
	v_pk_mul_f32 v[130:131], v[84:85], v[130:131] op_sel_hi:[1,0]
	v_pk_add_f32 v[156:157], v[156:157], 1.0 op_sel_hi:[1,0]
	s_nop 0
	v_rcp_f32_e32 v156, v156
	v_rcp_f32_e32 v157, v157
	s_nop 0
	v_pk_mul_f32 v[134:135], v[134:135], v[156:157]
	s_nop 0
	v_pk_mul_f32 v[154:155], v[154:155], v[134:135]
	v_pk_mul_f32 v[134:135], v[158:159], v[160:161]
	s_nop 0
	v_pk_mul_f32 v[156:157], v[130:131], v[134:135]
	s_nop 0
	s_nop 0
	s_nop 0
	s_nop 0
	v_cvt_pk_bf16_f32 v131, v152, v153
	v_cndmask_b32_e64 v152, 0, 1, s[52:53]
	v_cvt_pk_bf16_f32 v130, v132, v133
	v_cvt_pk_bf16_f32 v132, v154, v155
	v_cvt_pk_bf16_f32 v133, v156, v157
	v_cmp_ne_u32_e64 s[10:11], 1, v152
	s_mov_b64 s[52:53], -1
	s_cbranch_vccnz .Lcr1_2132
	s_mov_b64 s[52:53], 0
	global_store_dwordx4 v[172:173], v[130:133], off offset:-2048

.Lcr1_2134:
	s_waitcnt lgkmcnt(5)
	s_nop 0
	s_nop 0
	v_mov_b32_e32 v130, v246
	s_and_b64 vcc, exec, s[10:11]
	s_mov_b64 s[52:53], -1
	v_pk_mul_f32 v[132:133], v[110:111], v[130:131] op_sel_hi:[1,0]
	v_pk_mul_f32 v[152:153], v[112:113], v[130:131] op_sel_hi:[1,0]
	v_pk_mul_f32 v[150:151], v[132:133], s[30:31] op_sel_hi:[1,0]
	v_pk_mul_f32 v[154:155], v[152:153], s[30:31] op_sel_hi:[1,0]
	v_exp_f32_e32 v150, v150
	v_exp_f32_e32 v151, v151
	v_exp_f32_e32 v154, v154
	v_exp_f32_e32 v155, v155
	v_pk_mul_f32 v[134:135], v[78:79], v[130:131] op_sel_hi:[1,0]
	v_pk_add_f32 v[150:151], v[150:151], 1.0 op_sel_hi:[1,0]
	v_pk_mul_f32 v[156:157], v[108:109], v[130:131] op_sel_hi:[1,0]
	v_rcp_f32_e32 v150, v150
	v_rcp_f32_e32 v151, v151
	v_pk_add_f32 v[154:155], v[154:155], 1.0 op_sel_hi:[1,0]
	v_pk_mul_f32 v[158:159], v[156:157], s[30:31] op_sel_hi:[1,0]
	v_rcp_f32_e32 v154, v154
	v_rcp_f32_e32 v155, v155
	v_pk_mul_f32 v[132:133], v[132:133], v[150:151]
	v_exp_f32_e32 v158, v158
	v_pk_mul_f32 v[132:133], v[134:135], v[132:133]
	v_pk_mul_f32 v[134:135], v[80:81], v[130:131] op_sel_hi:[1,0]
	v_pk_mul_f32 v[150:151], v[152:153], v[154:155]
	v_exp_f32_e32 v159, v159
	v_pk_mul_f32 v[150:151], v[134:135], v[150:151]
	v_pk_mul_f32 v[134:135], v[106:107], v[130:131] op_sel_hi:[1,0]
	v_pk_mul_f32 v[152:153], v[74:75], v[130:131] op_sel_hi:[1,0]
	v_pk_mul_f32 v[154:155], v[134:135], s[30:31] op_sel_hi:[1,0]
	v_pk_add_f32 v[158:159], v[158:159], 1.0 op_sel_hi:[1,0]
	v_exp_f32_e32 v154, v154
	v_exp_f32_e32 v155, v155
	v_rcp_f32_e32 v158, v158
	v_rcp_f32_e32 v159, v159
	v_pk_mul_f32 v[130:131], v[76:77], v[130:131] op_sel_hi:[1,0]
	v_pk_add_f32 v[154:155], v[154:155], 1.0 op_sel_hi:[1,0]
	s_nop 0
	v_rcp_f32_e32 v154, v154
	v_rcp_f32_e32 v155, v155
	s_nop 0
	v_pk_mul_f32 v[134:135], v[134:135], v[154:155]
	s_nop 0
	v_pk_mul_f32 v[152:153], v[152:153], v[134:135]
	v_pk_mul_f32 v[134:135], v[156:157], v[158:159]
	s_nop 0
	v_pk_mul_f32 v[154:155], v[130:131], v[134:135]
	v_cvt_pk_bf16_f32 v130, v132, v133
	v_cvt_pk_bf16_f32 v131, v150, v151
	v_cvt_pk_bf16_f32 v132, v152, v153
	v_cvt_pk_bf16_f32 v133, v154, v155
	s_cbranch_vccnz .Lcr1_2136
	s_mov_b64 s[52:53], 0
	global_store_dwordx4 v[172:173], v[130:133], off

.Lcr1_2138:
	s_waitcnt lgkmcnt(4)
	s_nop 0
	s_nop 0
	v_mov_b32_e32 v130, v247
	s_and_b64 vcc, exec, s[10:11]
	s_mov_b64 s[52:53], -1
	v_pk_mul_f32 v[132:133], v[102:103], v[130:131] op_sel_hi:[1,0]
	v_pk_mul_f32 v[150:151], v[104:105], v[130:131] op_sel_hi:[1,0]
	v_pk_mul_f32 v[148:149], v[132:133], s[30:31] op_sel_hi:[1,0]
	v_pk_mul_f32 v[152:153], v[150:151], s[30:31] op_sel_hi:[1,0]
	v_exp_f32_e32 v148, v148
	v_exp_f32_e32 v149, v149
	v_exp_f32_e32 v152, v152
	v_exp_f32_e32 v153, v153
	v_pk_mul_f32 v[134:135], v[70:71], v[130:131] op_sel_hi:[1,0]
	v_pk_add_f32 v[148:149], v[148:149], 1.0 op_sel_hi:[1,0]
	v_pk_mul_f32 v[154:155], v[100:101], v[130:131] op_sel_hi:[1,0]
	v_rcp_f32_e32 v148, v148
	v_rcp_f32_e32 v149, v149
	v_pk_add_f32 v[152:153], v[152:153], 1.0 op_sel_hi:[1,0]
	v_pk_mul_f32 v[156:157], v[154:155], s[30:31] op_sel_hi:[1,0]
	v_rcp_f32_e32 v152, v152
	v_rcp_f32_e32 v153, v153
	v_pk_mul_f32 v[132:133], v[132:133], v[148:149]
	v_exp_f32_e32 v156, v156
	v_pk_mul_f32 v[132:133], v[134:135], v[132:133]
	v_pk_mul_f32 v[134:135], v[72:73], v[130:131] op_sel_hi:[1,0]
	v_pk_mul_f32 v[148:149], v[150:151], v[152:153]
	v_exp_f32_e32 v157, v157
	v_pk_mul_f32 v[148:149], v[134:135], v[148:149]
	v_pk_mul_f32 v[134:135], v[98:99], v[130:131] op_sel_hi:[1,0]
	v_pk_mul_f32 v[150:151], v[66:67], v[130:131] op_sel_hi:[1,0]
	v_pk_mul_f32 v[152:153], v[134:135], s[30:31] op_sel_hi:[1,0]
	v_pk_add_f32 v[156:157], v[156:157], 1.0 op_sel_hi:[1,0]
	v_exp_f32_e32 v152, v152
	v_exp_f32_e32 v153, v153
	v_rcp_f32_e32 v156, v156
	v_rcp_f32_e32 v157, v157
	v_pk_mul_f32 v[130:131], v[68:69], v[130:131] op_sel_hi:[1,0]
	v_pk_add_f32 v[152:153], v[152:153], 1.0 op_sel_hi:[1,0]
	s_nop 0
	v_rcp_f32_e32 v152, v152
	v_rcp_f32_e32 v153, v153
	s_nop 0
	v_pk_mul_f32 v[134:135], v[134:135], v[152:153]
	s_nop 0
	v_pk_mul_f32 v[150:151], v[150:151], v[134:135]
	v_pk_mul_f32 v[134:135], v[154:155], v[156:157]
	s_nop 0
	v_pk_mul_f32 v[152:153], v[130:131], v[134:135]
	v_cvt_pk_bf16_f32 v130, v132, v133
	v_cvt_pk_bf16_f32 v131, v148, v149
	v_cvt_pk_bf16_f32 v132, v150, v151
	v_cvt_pk_bf16_f32 v133, v152, v153
	s_cbranch_vccnz .Lcr1_2140
	s_mov_b64 s[52:53], 0
	global_store_dwordx4 v[172:173], v[130:133], off offset:2048

.Lcr1_2142:
	s_waitcnt lgkmcnt(3)
	s_nop 0
	s_nop 0
	v_mov_b32_e32 v130, v250
	s_nop 0
	s_and_b64 vcc, exec, s[10:11]
	v_pk_mul_f32 v[132:133], v[62:63], v[130:131] op_sel_hi:[1,0]
	v_pk_mul_f32 v[150:151], v[64:65], v[130:131] op_sel_hi:[1,0]
	v_pk_mul_f32 v[148:149], v[132:133], s[30:31] op_sel_hi:[1,0]
	v_pk_mul_f32 v[152:153], v[150:151], s[30:31] op_sel_hi:[1,0]
	v_exp_f32_e32 v148, v148
	v_exp_f32_e32 v149, v149
	v_exp_f32_e32 v152, v152
	v_exp_f32_e32 v153, v153
	v_pk_mul_f32 v[134:135], v[30:31], v[130:131] op_sel_hi:[1,0]
	v_pk_add_f32 v[148:149], v[148:149], 1.0 op_sel_hi:[1,0]
	v_pk_mul_f32 v[154:155], v[60:61], v[130:131] op_sel_hi:[1,0]
	v_rcp_f32_e32 v148, v148
	v_rcp_f32_e32 v149, v149
	v_pk_add_f32 v[152:153], v[152:153], 1.0 op_sel_hi:[1,0]
	v_pk_mul_f32 v[156:157], v[154:155], s[30:31] op_sel_hi:[1,0]
	v_rcp_f32_e32 v152, v152
	v_rcp_f32_e32 v153, v153
	v_pk_mul_f32 v[132:133], v[132:133], v[148:149]
	v_exp_f32_e32 v156, v156
	v_pk_mul_f32 v[132:133], v[134:135], v[132:133]
	v_pk_mul_f32 v[134:135], v[32:33], v[130:131] op_sel_hi:[1,0]
	v_pk_mul_f32 v[148:149], v[150:151], v[152:153]
	v_exp_f32_e32 v157, v157
	v_pk_mul_f32 v[148:149], v[134:135], v[148:149]
	v_pk_mul_f32 v[134:135], v[58:59], v[130:131] op_sel_hi:[1,0]
	v_pk_mul_f32 v[150:151], v[26:27], v[130:131] op_sel_hi:[1,0]
	v_pk_mul_f32 v[152:153], v[134:135], s[30:31] op_sel_hi:[1,0]
	v_pk_add_f32 v[156:157], v[156:157], 1.0 op_sel_hi:[1,0]
	v_exp_f32_e32 v152, v152
	v_exp_f32_e32 v153, v153
	v_rcp_f32_e32 v156, v156
	v_rcp_f32_e32 v157, v157
	v_pk_mul_f32 v[130:131], v[28:29], v[130:131] op_sel_hi:[1,0]
	v_pk_add_f32 v[152:153], v[152:153], 1.0 op_sel_hi:[1,0]
	s_mov_b64 s[52:53], -1
	v_rcp_f32_e32 v152, v152
	v_rcp_f32_e32 v153, v153
	s_nop 0
	v_pk_mul_f32 v[134:135], v[134:135], v[152:153]
	s_nop 0
	v_pk_mul_f32 v[150:151], v[150:151], v[134:135]
	v_pk_mul_f32 v[134:135], v[154:155], v[156:157]
	s_nop 0
	v_pk_mul_f32 v[152:153], v[130:131], v[134:135]
	v_cvt_pk_bf16_f32 v130, v132, v133
	v_cvt_pk_bf16_f32 v131, v148, v149
	v_cvt_pk_bf16_f32 v132, v150, v151
	v_cvt_pk_bf16_f32 v133, v152, v153
	s_mov_b32 s98, 0x5000
	s_mov_b32 s99, 0x0
	v_lshl_add_u64 v[172:173], v[170:171], 0, s[98:99]
	s_cbranch_vccnz .Lcr1_2144
	s_mov_b64 s[52:53], 0
	global_store_dwordx4 v[172:173], v[130:133], off offset:-4096

.Lcr1_2146:
	s_waitcnt lgkmcnt(2)
	s_nop 0
	s_nop 0
	v_mov_b32_e32 v130, v251
	s_and_b64 vcc, exec, s[10:11]
	s_mov_b64 s[52:53], -1
	v_pk_mul_f32 v[132:133], v[54:55], v[130:131] op_sel_hi:[1,0]
	v_pk_mul_f32 v[146:147], v[56:57], v[130:131] op_sel_hi:[1,0]
	v_pk_mul_f32 v[144:145], v[132:133], s[30:31] op_sel_hi:[1,0]
	v_pk_mul_f32 v[148:149], v[146:147], s[30:31] op_sel_hi:[1,0]
	v_exp_f32_e32 v144, v144
	v_exp_f32_e32 v145, v145
	v_exp_f32_e32 v148, v148
	v_exp_f32_e32 v149, v149
	v_pk_mul_f32 v[134:135], v[22:23], v[130:131] op_sel_hi:[1,0]
	v_pk_add_f32 v[144:145], v[144:145], 1.0 op_sel_hi:[1,0]
	v_pk_mul_f32 v[150:151], v[52:53], v[130:131] op_sel_hi:[1,0]
	v_rcp_f32_e32 v144, v144
	v_rcp_f32_e32 v145, v145
	v_pk_add_f32 v[148:149], v[148:149], 1.0 op_sel_hi:[1,0]
	v_pk_mul_f32 v[152:153], v[150:151], s[30:31] op_sel_hi:[1,0]
	v_rcp_f32_e32 v148, v148
	v_rcp_f32_e32 v149, v149
	v_pk_mul_f32 v[132:133], v[132:133], v[144:145]
	v_exp_f32_e32 v152, v152
	v_pk_mul_f32 v[132:133], v[134:135], v[132:133]
	v_pk_mul_f32 v[134:135], v[24:25], v[130:131] op_sel_hi:[1,0]
	v_pk_mul_f32 v[144:145], v[146:147], v[148:149]
	v_exp_f32_e32 v153, v153
	v_pk_mul_f32 v[144:145], v[134:135], v[144:145]
	v_pk_mul_f32 v[134:135], v[50:51], v[130:131] op_sel_hi:[1,0]
	v_pk_mul_f32 v[146:147], v[18:19], v[130:131] op_sel_hi:[1,0]
	v_pk_mul_f32 v[148:149], v[134:135], s[30:31] op_sel_hi:[1,0]
	v_pk_add_f32 v[152:153], v[152:153], 1.0 op_sel_hi:[1,0]
	v_exp_f32_e32 v148, v148
	v_exp_f32_e32 v149, v149
	v_rcp_f32_e32 v152, v152
	v_rcp_f32_e32 v153, v153
	v_pk_mul_f32 v[130:131], v[20:21], v[130:131] op_sel_hi:[1,0]
	v_pk_add_f32 v[148:149], v[148:149], 1.0 op_sel_hi:[1,0]
	s_nop 0
	v_rcp_f32_e32 v148, v148
	v_rcp_f32_e32 v149, v149
	s_nop 0
	v_pk_mul_f32 v[134:135], v[134:135], v[148:149]
	s_nop 0
	v_pk_mul_f32 v[146:147], v[146:147], v[134:135]
	v_pk_mul_f32 v[134:135], v[150:151], v[152:153]
	s_nop 0
	v_pk_mul_f32 v[148:149], v[130:131], v[134:135]
	v_cvt_pk_bf16_f32 v130, v132, v133
	v_cvt_pk_bf16_f32 v131, v144, v145
	v_cvt_pk_bf16_f32 v132, v146, v147
	v_cvt_pk_bf16_f32 v133, v148, v149
	s_cbranch_vccnz .Lcr1_2148
	s_mov_b64 s[52:53], 0
	global_store_dwordx4 v[172:173], v[130:133], off offset:-2048

.Lcr1_2150:
	s_waitcnt lgkmcnt(1)
	s_nop 0
	s_nop 0
	v_mov_b32_e32 v130, v252
	s_and_b64 vcc, exec, s[10:11]
	s_mov_b64 s[52:53], -1
	v_pk_mul_f32 v[132:133], v[46:47], v[130:131] op_sel_hi:[1,0]
	v_pk_mul_f32 v[144:145], v[48:49], v[130:131] op_sel_hi:[1,0]
	v_pk_mul_f32 v[142:143], v[132:133], s[30:31] op_sel_hi:[1,0]
	v_pk_mul_f32 v[146:147], v[144:145], s[30:31] op_sel_hi:[1,0]
	v_exp_f32_e32 v142, v142
	v_exp_f32_e32 v143, v143
	v_exp_f32_e32 v146, v146
	v_exp_f32_e32 v147, v147
	v_pk_mul_f32 v[134:135], v[14:15], v[130:131] op_sel_hi:[1,0]
	v_pk_add_f32 v[142:143], v[142:143], 1.0 op_sel_hi:[1,0]
	v_pk_mul_f32 v[148:149], v[44:45], v[130:131] op_sel_hi:[1,0]
	v_rcp_f32_e32 v142, v142
	v_rcp_f32_e32 v143, v143
	v_pk_add_f32 v[146:147], v[146:147], 1.0 op_sel_hi:[1,0]
	v_pk_mul_f32 v[150:151], v[148:149], s[30:31] op_sel_hi:[1,0]
	v_rcp_f32_e32 v146, v146
	v_rcp_f32_e32 v147, v147
	v_pk_mul_f32 v[132:133], v[132:133], v[142:143]
	v_exp_f32_e32 v150, v150
	v_pk_mul_f32 v[132:133], v[134:135], v[132:133]
	v_pk_mul_f32 v[134:135], v[16:17], v[130:131] op_sel_hi:[1,0]
	v_pk_mul_f32 v[142:143], v[144:145], v[146:147]
	v_exp_f32_e32 v151, v151
	v_pk_mul_f32 v[142:143], v[134:135], v[142:143]
	v_pk_mul_f32 v[134:135], v[42:43], v[130:131] op_sel_hi:[1,0]
	v_pk_mul_f32 v[144:145], v[10:11], v[130:131] op_sel_hi:[1,0]
	v_pk_mul_f32 v[146:147], v[134:135], s[30:31] op_sel_hi:[1,0]
	v_pk_add_f32 v[150:151], v[150:151], 1.0 op_sel_hi:[1,0]
	v_exp_f32_e32 v146, v146
	v_exp_f32_e32 v147, v147
	v_rcp_f32_e32 v150, v150
	v_rcp_f32_e32 v151, v151
	v_pk_mul_f32 v[130:131], v[12:13], v[130:131] op_sel_hi:[1,0]
	v_pk_add_f32 v[146:147], v[146:147], 1.0 op_sel_hi:[1,0]
	s_nop 0
	v_rcp_f32_e32 v146, v146
	v_rcp_f32_e32 v147, v147
	s_nop 0
	v_pk_mul_f32 v[134:135], v[134:135], v[146:147]
	s_nop 0
	v_pk_mul_f32 v[144:145], v[144:145], v[134:135]
	v_pk_mul_f32 v[134:135], v[148:149], v[150:151]
	s_nop 0
	v_pk_mul_f32 v[146:147], v[130:131], v[134:135]
	v_cvt_pk_bf16_f32 v130, v132, v133
	v_cvt_pk_bf16_f32 v131, v142, v143
	v_cvt_pk_bf16_f32 v132, v144, v145
	v_cvt_pk_bf16_f32 v133, v146, v147
	s_cbranch_vccnz .Lcr1_2152
	s_mov_b64 s[52:53], 0
	global_store_dwordx4 v[172:173], v[130:133], off

.Lcr1_2154:
	s_waitcnt lgkmcnt(0)
	s_nop 0
	s_nop 0
	v_mov_b32_e32 v130, v253
	s_and_b64 vcc, exec, s[10:11]
	s_mov_b64 s[10:11], -1
	v_pk_mul_f32 v[132:133], v[38:39], v[130:131] op_sel_hi:[1,0]
	v_pk_mul_f32 v[142:143], v[40:41], v[130:131] op_sel_hi:[1,0]
	v_pk_mul_f32 v[140:141], v[132:133], s[30:31] op_sel_hi:[1,0]
	v_pk_mul_f32 v[144:145], v[142:143], s[30:31] op_sel_hi:[1,0]
	v_exp_f32_e32 v140, v140
	v_exp_f32_e32 v141, v141
	v_exp_f32_e32 v144, v144
	v_exp_f32_e32 v145, v145
	v_pk_mul_f32 v[134:135], v[6:7], v[130:131] op_sel_hi:[1,0]
	v_pk_add_f32 v[140:141], v[140:141], 1.0 op_sel_hi:[1,0]
	v_pk_mul_f32 v[146:147], v[36:37], v[130:131] op_sel_hi:[1,0]
	v_rcp_f32_e32 v140, v140
	v_rcp_f32_e32 v141, v141
	v_pk_add_f32 v[144:145], v[144:145], 1.0 op_sel_hi:[1,0]
	v_pk_mul_f32 v[148:149], v[146:147], s[30:31] op_sel_hi:[1,0]
	v_rcp_f32_e32 v144, v144
	v_rcp_f32_e32 v145, v145
	v_pk_mul_f32 v[132:133], v[132:133], v[140:141]
	v_exp_f32_e32 v148, v148
	v_pk_mul_f32 v[132:133], v[134:135], v[132:133]
	v_pk_mul_f32 v[134:135], v[8:9], v[130:131] op_sel_hi:[1,0]
	v_pk_mul_f32 v[140:141], v[142:143], v[144:145]
	v_exp_f32_e32 v149, v149
	v_pk_mul_f32 v[140:141], v[134:135], v[140:141]
	v_pk_mul_f32 v[134:135], v[34:35], v[130:131] op_sel_hi:[1,0]
	v_pk_mul_f32 v[142:143], v[2:3], v[130:131] op_sel_hi:[1,0]
	v_pk_mul_f32 v[144:145], v[134:135], s[30:31] op_sel_hi:[1,0]
	v_pk_add_f32 v[148:149], v[148:149], 1.0 op_sel_hi:[1,0]
	v_exp_f32_e32 v144, v144
	v_exp_f32_e32 v145, v145
	v_rcp_f32_e32 v148, v148
	v_rcp_f32_e32 v149, v149
	v_pk_mul_f32 v[130:131], v[4:5], v[130:131] op_sel_hi:[1,0]
	v_pk_add_f32 v[144:145], v[144:145], 1.0 op_sel_hi:[1,0]
	s_nop 0
	v_rcp_f32_e32 v144, v144
	v_rcp_f32_e32 v145, v145
	s_nop 0
	v_pk_mul_f32 v[134:135], v[134:135], v[144:145]
	s_nop 0
	v_pk_mul_f32 v[142:143], v[142:143], v[134:135]
	v_pk_mul_f32 v[134:135], v[146:147], v[148:149]
	s_nop 0
	v_pk_mul_f32 v[144:145], v[130:131], v[134:135]
	v_cvt_pk_bf16_f32 v130, v132, v133
	v_cvt_pk_bf16_f32 v131, v140, v141
	v_cvt_pk_bf16_f32 v132, v142, v143
	v_cvt_pk_bf16_f32 v133, v144, v145
	s_cbranch_vccnz .Lcr1_2156
	s_mov_b64 s[10:11], 0
	global_store_dwordx4 v[172:173], v[130:133], off offset:2048
.Lcr1_2156:
	s_andn2_b64 vcc, exec, s[10:11]
	s_cbranch_vccnz .LBB0_2158
	global_store_dwordx4 v[172:173], v[130:133], off offset:2048 sc1
	s_nop 1
	s_branch .LBB0_2158
.Lcr1_slow:
	s_mov_b32 s100, s82
	s_and_b64 vcc, exec, s[24:25]
	s_cbranch_vccz .LBB0_2126
	s_barrier
.LBB0_2126:
	v_mov_b32_e32 v137, v210
	v_mov_b32_e32 v130, v202
	v_xor_b32_e32 v138, 32, v204
	v_add_u32_e32 v136, s68, v130
	v_lshl_add_u32 v130, s82, 8, v136
	v_lshlrev_b32_e32 v132, 2, v137
	v_ashrrev_i32_e32 v133, 31, v132
	v_ashrrev_i32_e32 v131, 31, v130
	v_lshl_add_u64 v[132:133], v[132:133], 2, s[2:3]
	v_lshlrev_b64 v[130:131], 6, v[130:131]
	v_lshl_add_u64 v[134:135], v[132:133], 0, v[130:131]
	v_lshl_add_u64 v[170:171], v[134:135], 0, 0
	global_load_dwordx4 v[130:133], v[134:135], off
	s_mov_b32 s98, 0x1000
	s_mov_b32 s99, 0x0
	v_lshl_add_u64 v[172:173], v[170:171], 0, s[98:99]
	global_load_dwordx4 v[140:143], v[172:173], off offset:-3072
	global_load_dwordx4 v[144:147], v[172:173], off offset:-2048
	global_load_dwordx4 v[148:151], v[172:173], off offset:-1024
	v_add_co_u32_e32 v134, vcc, s13, v134
	s_mul_i32 s10, s82, 44
	s_nop 0
	v_addc_co_u32_e32 v135, vcc, 0, v135, vcc
	global_load_dwordx4 v[152:155], v[134:135], off
	global_load_dwordx4 v[156:159], v[134:135], off offset:1024
	global_load_dwordx4 v[160:163], v[134:135], off offset:2048
	global_load_dwordx4 v[164:167], v[134:135], off offset:3072
	v_and_b32_e32 v135, 64, v204
	v_xor_b32_e32 v134, 16, v204
	v_add_u32_e32 v135, 64, v135
	v_cmp_lt_i32_e32 vcc, v134, v135
	s_lshl_b32 s11, s12, 1
	s_add_i32 s10, s10, s11
	v_cndmask_b32_e32 v134, v204, v134, vcc
	v_cmp_lt_i32_e32 vcc, v138, v135
	v_lshlrev_b32_e32 v139, 2, v134
	s_or_b32 s10, s10, s74
	v_cndmask_b32_e32 v135, v204, v138, vcc
	v_lshlrev_b32_e32 v168, 2, v135
	s_ashr_i32 s11, s10, 31
	v_lshl_add_u32 v138, v137, 3, s75
	s_lshl_b64 s[10:11], s[10:11], 15
	v_lshlrev_b32_e32 v137, 4, v137
	v_ashrrev_i32_e32 v138, 5, v138
	s_add_u32 s50, s65, s10
	v_and_b32_e32 v137, 48, v137
	s_addc_u32 s51, s66, s11
	s_cmpk_lt_i32 s82, 0x80
	s_cselect_b64 s[52:53], -1, 0
	s_xor_b64 s[54:55], s[36:37], -1
	s_and_b64 s[52:53], s[54:55], s[52:53]
	s_mov_b64 s[10:11], -1
	s_and_b64 vcc, exec, s[52:53]
	s_waitcnt vmcnt(7)
	v_mov_b32_e32 v134, v131
	v_mov_b32_e32 v135, v132
	v_mov_b32_e32 v131, v133
	s_waitcnt vmcnt(6)
	v_add_f32_e32 v132, v140, v141
	v_add_f32_e32 v133, v142, v143
	s_waitcnt vmcnt(5)
	v_add_f32_e32 v140, v144, v145
	v_add_f32_e32 v141, v146, v147
	s_waitcnt vmcnt(4)
	v_add_f32_e32 v142, v148, v149
	v_add_f32_e32 v143, v150, v151
	v_pk_add_f32 v[130:131], v[134:135], v[130:131]
	v_add_f32_e32 v132, v132, v133
	v_add_f32_e32 v133, v140, v141
	v_add_f32_e32 v134, v142, v143
	s_waitcnt vmcnt(3)
	v_add_f32_e32 v135, v152, v153
	v_add_f32_e32 v140, v154, v155
	s_waitcnt vmcnt(2)
	v_add_f32_e32 v141, v156, v157
	v_add_f32_e32 v142, v158, v159
	s_waitcnt vmcnt(1)
	v_add_f32_e32 v143, v160, v161
	v_add_f32_e32 v144, v162, v163
	v_add_f32_e32 v130, v130, v131
	v_add_f32_e32 v135, v135, v140
	v_add_f32_e32 v140, v141, v142
	v_add_f32_e32 v141, v143, v144
	ds_bpermute_b32 v143, v139, v130
	ds_bpermute_b32 v131, v139, v132
	ds_bpermute_b32 v148, v139, v134
	ds_bpermute_b32 v144, v139, v135
	ds_bpermute_b32 v147, v139, v133
	s_waitcnt lgkmcnt(4)
	v_add_f32_e32 v130, v130, v143
	s_waitcnt lgkmcnt(3)
	v_add_f32_e32 v152, v132, v131
	ds_bpermute_b32 v131, v168, v130
	ds_bpermute_b32 v154, v139, v141
	s_waitcnt vmcnt(0)
	v_add_f32_e32 v145, v164, v165
	v_add_f32_e32 v146, v166, v167
	v_add_f32_e32 v142, v145, v146
	s_waitcnt lgkmcnt(1)
	v_add_f32_e32 v130, v130, v131
	v_fmamk_f32 v130, v130, 0x3a800000, v205
	v_rsq_f32_e32 v130, v130
	v_add_f32_e32 v148, v134, v148
	v_add_f32_e32 v145, v135, v144
	v_add_f32_e32 v150, v133, v147
	v_mov_b32_e32 v244, v130
	v_pk_mul_f32 v[134:135], v[128:129], v[130:131] op_sel_hi:[1,0]
	v_pk_mul_f32 v[132:133], v[126:127], v[130:131] op_sel_hi:[1,0]
	v_pk_mul_f32 v[156:157], v[134:135], s[30:31] op_sel_hi:[1,0]
	s_waitcnt lgkmcnt(0)
	v_add_f32_e32 v141, v141, v154
	v_pk_mul_f32 v[154:155], v[132:133], s[30:31] op_sel_hi:[1,0]
	v_exp_f32_e32 v156, v156
	v_exp_f32_e32 v157, v157
	v_exp_f32_e32 v154, v154
	v_exp_f32_e32 v155, v155
	v_pk_mul_f32 v[160:161], v[96:97], v[130:131] op_sel_hi:[1,0]
	v_pk_add_f32 v[156:157], v[156:157], 1.0 op_sel_hi:[1,0]
	v_pk_mul_f32 v[162:163], v[122:123], v[130:131] op_sel_hi:[1,0]
	v_pk_add_f32 v[154:155], v[154:155], 1.0 op_sel_hi:[1,0]
	v_rcp_f32_e32 v156, v156
	v_rcp_f32_e32 v157, v157
	v_rcp_f32_e32 v154, v154
	v_rcp_f32_e32 v155, v155
	v_pk_mul_f32 v[158:159], v[94:95], v[130:131] op_sel_hi:[1,0]
	v_pk_mul_f32 v[134:135], v[134:135], v[156:157]
	v_pk_mul_f32 v[156:157], v[124:125], v[130:131] op_sel_hi:[1,0]
	v_pk_mul_f32 v[132:133], v[132:133], v[154:155]
	v_pk_mul_f32 v[154:155], v[160:161], v[134:135]
	v_pk_mul_f32 v[134:135], v[162:163], s[30:31] op_sel_hi:[1,0]
	v_pk_mul_f32 v[132:133], v[158:159], v[132:133]
	v_exp_f32_e32 v134, v134
	v_exp_f32_e32 v135, v135
	v_pk_mul_f32 v[158:159], v[156:157], s[30:31] op_sel_hi:[1,0]
	ds_bpermute_b32 v146, v139, v140
	v_exp_f32_e32 v158, v158
	v_exp_f32_e32 v159, v159
	v_pk_add_f32 v[134:135], v[134:135], 1.0 op_sel_hi:[1,0]
	ds_bpermute_b32 v139, v139, v142
	v_rcp_f32_e32 v134, v134
	v_rcp_f32_e32 v135, v135
	v_pk_add_f32 v[158:159], v[158:159], 1.0 op_sel_hi:[1,0]
	v_pk_mul_f32 v[164:165], v[90:91], v[130:131] op_sel_hi:[1,0]
	v_rcp_f32_e32 v158, v158
	v_rcp_f32_e32 v159, v159
	v_pk_mul_f32 v[134:135], v[162:163], v[134:135]
	v_pk_mul_f32 v[130:131], v[92:93], v[130:131] op_sel_hi:[1,0]
	v_pk_mul_f32 v[160:161], v[164:165], v[134:135]
	v_pk_mul_f32 v[134:135], v[156:157], v[158:159]
	s_waitcnt lgkmcnt(1)
	v_add_f32_e32 v143, v140, v146
	v_pk_mul_f32 v[156:157], v[130:131], v[134:135]
	v_lshrrev_b32_e32 v131, 3, v136
	s_waitcnt lgkmcnt(0)
	v_add_f32_e32 v139, v142, v139
	v_lshlrev_b32_e32 v130, 7, v136
	v_and_b32_e32 v131, 14, v131
	ds_bpermute_b32 v153, v168, v152
	ds_bpermute_b32 v151, v168, v150
	ds_bpermute_b32 v149, v168, v148
	ds_bpermute_b32 v146, v168, v145
	ds_bpermute_b32 v144, v168, v143
	ds_bpermute_b32 v142, v168, v141
	ds_bpermute_b32 v140, v168, v139
	v_and_b32_e32 v130, 0xffffc000, v130
	v_lshlrev_b32_e32 v134, 6, v136
	v_add_lshl_u32 v147, v131, v138, 10
	v_lshlrev_b32_e32 v131, 2, v136
	v_and_or_b32 v134, v134, s69, v137
	v_and_b32_e32 v131, 32, v131
	v_add_u32_e32 v130, v147, v130
	v_bitop3_b32 v130, v130, v134, v131 bitop3:0xf6
	v_ashrrev_i32_e32 v131, 31, v130
	v_lshl_add_u64 v[134:135], s[50:51], 0, v[130:131]
	v_cvt_pk_bf16_f32 v130, v132, v133
	v_cvt_pk_bf16_f32 v131, v154, v155
	v_cvt_pk_bf16_f32 v132, v160, v161
	v_cvt_pk_bf16_f32 v133, v156, v157
	v_lshl_add_u64 v[170:171], v[134:135], 0, 0
	s_cbranch_vccz .LBB0_2128
	global_store_dwordx4 v[134:135], v[130:133], off
	s_mov_b64 s[10:11], 0

.LBB0_2130:
	s_waitcnt lgkmcnt(6)
	v_add_f32_e32 v130, v152, v153
	v_fmamk_f32 v130, v130, 0x3a800000, v205
	v_rsq_f32_e32 v130, v130
	s_andn2_b64 vcc, exec, s[52:53]
	v_mov_b32_e32 v245, v130
	v_pk_mul_f32 v[132:133], v[118:119], v[130:131] op_sel_hi:[1,0]
	s_nop 0
	v_pk_mul_f32 v[152:153], v[132:133], s[30:31] op_sel_hi:[1,0]
	v_pk_mul_f32 v[154:155], v[120:121], v[130:131] op_sel_hi:[1,0]
	v_exp_f32_e32 v152, v152
	v_exp_f32_e32 v153, v153
	v_pk_mul_f32 v[156:157], v[154:155], s[30:31] op_sel_hi:[1,0]
	v_pk_mul_f32 v[134:135], v[86:87], v[130:131] op_sel_hi:[1,0]
	v_exp_f32_e32 v156, v156
	v_exp_f32_e32 v157, v157
	v_pk_add_f32 v[152:153], v[152:153], 1.0 op_sel_hi:[1,0]
	v_pk_mul_f32 v[158:159], v[116:117], v[130:131] op_sel_hi:[1,0]
	v_rcp_f32_e32 v152, v152
	v_rcp_f32_e32 v153, v153
	v_pk_add_f32 v[156:157], v[156:157], 1.0 op_sel_hi:[1,0]
	v_pk_mul_f32 v[160:161], v[158:159], s[30:31] op_sel_hi:[1,0]
	v_rcp_f32_e32 v156, v156
	v_rcp_f32_e32 v157, v157
	v_pk_mul_f32 v[132:133], v[132:133], v[152:153]
	v_exp_f32_e32 v160, v160
	v_pk_mul_f32 v[132:133], v[134:135], v[132:133]
	v_pk_mul_f32 v[134:135], v[88:89], v[130:131] op_sel_hi:[1,0]
	v_pk_mul_f32 v[152:153], v[154:155], v[156:157]
	v_exp_f32_e32 v161, v161
	v_pk_mul_f32 v[152:153], v[134:135], v[152:153]
	v_pk_mul_f32 v[134:135], v[114:115], v[130:131] op_sel_hi:[1,0]
	v_pk_mul_f32 v[154:155], v[82:83], v[130:131] op_sel_hi:[1,0]
	v_pk_mul_f32 v[156:157], v[134:135], s[30:31] op_sel_hi:[1,0]
	v_pk_add_f32 v[160:161], v[160:161], 1.0 op_sel_hi:[1,0]
	v_exp_f32_e32 v156, v156
	v_exp_f32_e32 v157, v157
	v_rcp_f32_e32 v160, v160
	v_rcp_f32_e32 v161, v161
	v_pk_mul_f32 v[130:131], v[84:85], v[130:131] op_sel_hi:[1,0]
	v_pk_add_f32 v[156:157], v[156:157], 1.0 op_sel_hi:[1,0]
	s_nop 0
	v_rcp_f32_e32 v156, v156
	v_rcp_f32_e32 v157, v157
	s_nop 0
	v_pk_mul_f32 v[134:135], v[134:135], v[156:157]
	s_nop 0
	v_pk_mul_f32 v[154:155], v[154:155], v[134:135]
	v_pk_mul_f32 v[134:135], v[158:159], v[160:161]
	s_nop 0
	v_pk_mul_f32 v[156:157], v[130:131], v[134:135]
	s_nop 0
	s_nop 0
	s_nop 0
	s_nop 0
	v_cvt_pk_bf16_f32 v131, v152, v153
	v_cndmask_b32_e64 v152, 0, 1, s[52:53]
	v_cvt_pk_bf16_f32 v130, v132, v133
	v_cvt_pk_bf16_f32 v132, v154, v155
	v_cvt_pk_bf16_f32 v133, v156, v157
	v_cmp_ne_u32_e64 s[10:11], 1, v152
	s_mov_b64 s[52:53], -1
	s_cbranch_vccnz .LBB0_2132
	s_mov_b64 s[52:53], 0
	global_store_dwordx4 v[172:173], v[130:133], off offset:-2048

.LBB0_2134:
	s_waitcnt lgkmcnt(5)
	v_add_f32_e32 v130, v150, v151
	v_fmamk_f32 v130, v130, 0x3a800000, v205
	v_rsq_f32_e32 v130, v130
	s_and_b64 vcc, exec, s[10:11]
	s_mov_b64 s[52:53], -1
	v_mov_b32_e32 v246, v130
	v_pk_mul_f32 v[132:133], v[110:111], v[130:131] op_sel_hi:[1,0]
	v_pk_mul_f32 v[152:153], v[112:113], v[130:131] op_sel_hi:[1,0]
	v_pk_mul_f32 v[150:151], v[132:133], s[30:31] op_sel_hi:[1,0]
	v_pk_mul_f32 v[154:155], v[152:153], s[30:31] op_sel_hi:[1,0]
	v_exp_f32_e32 v150, v150
	v_exp_f32_e32 v151, v151
	v_exp_f32_e32 v154, v154
	v_exp_f32_e32 v155, v155
	v_pk_mul_f32 v[134:135], v[78:79], v[130:131] op_sel_hi:[1,0]
	v_pk_add_f32 v[150:151], v[150:151], 1.0 op_sel_hi:[1,0]
	v_pk_mul_f32 v[156:157], v[108:109], v[130:131] op_sel_hi:[1,0]
	v_rcp_f32_e32 v150, v150
	v_rcp_f32_e32 v151, v151
	v_pk_add_f32 v[154:155], v[154:155], 1.0 op_sel_hi:[1,0]
	v_pk_mul_f32 v[158:159], v[156:157], s[30:31] op_sel_hi:[1,0]
	v_rcp_f32_e32 v154, v154
	v_rcp_f32_e32 v155, v155
	v_pk_mul_f32 v[132:133], v[132:133], v[150:151]
	v_exp_f32_e32 v158, v158
	v_pk_mul_f32 v[132:133], v[134:135], v[132:133]
	v_pk_mul_f32 v[134:135], v[80:81], v[130:131] op_sel_hi:[1,0]
	v_pk_mul_f32 v[150:151], v[152:153], v[154:155]
	v_exp_f32_e32 v159, v159
	v_pk_mul_f32 v[150:151], v[134:135], v[150:151]
	v_pk_mul_f32 v[134:135], v[106:107], v[130:131] op_sel_hi:[1,0]
	v_pk_mul_f32 v[152:153], v[74:75], v[130:131] op_sel_hi:[1,0]
	v_pk_mul_f32 v[154:155], v[134:135], s[30:31] op_sel_hi:[1,0]
	v_pk_add_f32 v[158:159], v[158:159], 1.0 op_sel_hi:[1,0]
	v_exp_f32_e32 v154, v154
	v_exp_f32_e32 v155, v155
	v_rcp_f32_e32 v158, v158
	v_rcp_f32_e32 v159, v159
	v_pk_mul_f32 v[130:131], v[76:77], v[130:131] op_sel_hi:[1,0]
	v_pk_add_f32 v[154:155], v[154:155], 1.0 op_sel_hi:[1,0]
	s_nop 0
	v_rcp_f32_e32 v154, v154
	v_rcp_f32_e32 v155, v155
	s_nop 0
	v_pk_mul_f32 v[134:135], v[134:135], v[154:155]
	s_nop 0
	v_pk_mul_f32 v[152:153], v[152:153], v[134:135]
	v_pk_mul_f32 v[134:135], v[156:157], v[158:159]
	s_nop 0
	v_pk_mul_f32 v[154:155], v[130:131], v[134:135]
	v_cvt_pk_bf16_f32 v130, v132, v133
	v_cvt_pk_bf16_f32 v131, v150, v151
	v_cvt_pk_bf16_f32 v132, v152, v153
	v_cvt_pk_bf16_f32 v133, v154, v155
	s_cbranch_vccnz .LBB0_2136
	s_mov_b64 s[52:53], 0
	global_store_dwordx4 v[172:173], v[130:133], off

.LBB0_2138:
	s_waitcnt lgkmcnt(4)
	v_add_f32_e32 v130, v148, v149
	v_fmamk_f32 v130, v130, 0x3a800000, v205
	v_rsq_f32_e32 v130, v130
	s_and_b64 vcc, exec, s[10:11]
	s_mov_b64 s[52:53], -1
	v_mov_b32_e32 v247, v130
	v_pk_mul_f32 v[132:133], v[102:103], v[130:131] op_sel_hi:[1,0]
	v_pk_mul_f32 v[150:151], v[104:105], v[130:131] op_sel_hi:[1,0]
	v_pk_mul_f32 v[148:149], v[132:133], s[30:31] op_sel_hi:[1,0]
	v_pk_mul_f32 v[152:153], v[150:151], s[30:31] op_sel_hi:[1,0]
	v_exp_f32_e32 v148, v148
	v_exp_f32_e32 v149, v149
	v_exp_f32_e32 v152, v152
	v_exp_f32_e32 v153, v153
	v_pk_mul_f32 v[134:135], v[70:71], v[130:131] op_sel_hi:[1,0]
	v_pk_add_f32 v[148:149], v[148:149], 1.0 op_sel_hi:[1,0]
	v_pk_mul_f32 v[154:155], v[100:101], v[130:131] op_sel_hi:[1,0]
	v_rcp_f32_e32 v148, v148
	v_rcp_f32_e32 v149, v149
	v_pk_add_f32 v[152:153], v[152:153], 1.0 op_sel_hi:[1,0]
	v_pk_mul_f32 v[156:157], v[154:155], s[30:31] op_sel_hi:[1,0]
	v_rcp_f32_e32 v152, v152
	v_rcp_f32_e32 v153, v153
	v_pk_mul_f32 v[132:133], v[132:133], v[148:149]
	v_exp_f32_e32 v156, v156
	v_pk_mul_f32 v[132:133], v[134:135], v[132:133]
	v_pk_mul_f32 v[134:135], v[72:73], v[130:131] op_sel_hi:[1,0]
	v_pk_mul_f32 v[148:149], v[150:151], v[152:153]
	v_exp_f32_e32 v157, v157
	v_pk_mul_f32 v[148:149], v[134:135], v[148:149]
	v_pk_mul_f32 v[134:135], v[98:99], v[130:131] op_sel_hi:[1,0]
	v_pk_mul_f32 v[150:151], v[66:67], v[130:131] op_sel_hi:[1,0]
	v_pk_mul_f32 v[152:153], v[134:135], s[30:31] op_sel_hi:[1,0]
	v_pk_add_f32 v[156:157], v[156:157], 1.0 op_sel_hi:[1,0]
	v_exp_f32_e32 v152, v152
	v_exp_f32_e32 v153, v153
	v_rcp_f32_e32 v156, v156
	v_rcp_f32_e32 v157, v157
	v_pk_mul_f32 v[130:131], v[68:69], v[130:131] op_sel_hi:[1,0]
	v_pk_add_f32 v[152:153], v[152:153], 1.0 op_sel_hi:[1,0]
	s_nop 0
	v_rcp_f32_e32 v152, v152
	v_rcp_f32_e32 v153, v153
	s_nop 0
	v_pk_mul_f32 v[134:135], v[134:135], v[152:153]
	s_nop 0
	v_pk_mul_f32 v[150:151], v[150:151], v[134:135]
	v_pk_mul_f32 v[134:135], v[154:155], v[156:157]
	s_nop 0
	v_pk_mul_f32 v[152:153], v[130:131], v[134:135]
	v_cvt_pk_bf16_f32 v130, v132, v133
	v_cvt_pk_bf16_f32 v131, v148, v149
	v_cvt_pk_bf16_f32 v132, v150, v151
	v_cvt_pk_bf16_f32 v133, v152, v153
	s_cbranch_vccnz .LBB0_2140
	s_mov_b64 s[52:53], 0
	global_store_dwordx4 v[172:173], v[130:133], off offset:2048

.LBB0_2142:
	s_waitcnt lgkmcnt(3)
	v_add_f32_e32 v130, v145, v146
	v_fmamk_f32 v130, v130, 0x3a800000, v205
	v_rsq_f32_e32 v130, v130
	s_nop 0
	s_and_b64 vcc, exec, s[10:11]
	v_mov_b32_e32 v250, v130
	v_pk_mul_f32 v[132:133], v[62:63], v[130:131] op_sel_hi:[1,0]
	v_pk_mul_f32 v[150:151], v[64:65], v[130:131] op_sel_hi:[1,0]
	v_pk_mul_f32 v[148:149], v[132:133], s[30:31] op_sel_hi:[1,0]
	v_pk_mul_f32 v[152:153], v[150:151], s[30:31] op_sel_hi:[1,0]
	v_exp_f32_e32 v148, v148
	v_exp_f32_e32 v149, v149
	v_exp_f32_e32 v152, v152
	v_exp_f32_e32 v153, v153
	v_pk_mul_f32 v[134:135], v[30:31], v[130:131] op_sel_hi:[1,0]
	v_pk_add_f32 v[148:149], v[148:149], 1.0 op_sel_hi:[1,0]
	v_pk_mul_f32 v[154:155], v[60:61], v[130:131] op_sel_hi:[1,0]
	v_rcp_f32_e32 v148, v148
	v_rcp_f32_e32 v149, v149
	v_pk_add_f32 v[152:153], v[152:153], 1.0 op_sel_hi:[1,0]
	v_pk_mul_f32 v[156:157], v[154:155], s[30:31] op_sel_hi:[1,0]
	v_rcp_f32_e32 v152, v152
	v_rcp_f32_e32 v153, v153
	v_pk_mul_f32 v[132:133], v[132:133], v[148:149]
	v_exp_f32_e32 v156, v156
	v_pk_mul_f32 v[132:133], v[134:135], v[132:133]
	v_pk_mul_f32 v[134:135], v[32:33], v[130:131] op_sel_hi:[1,0]
	v_pk_mul_f32 v[148:149], v[150:151], v[152:153]
	v_exp_f32_e32 v157, v157
	v_pk_mul_f32 v[148:149], v[134:135], v[148:149]
	v_pk_mul_f32 v[134:135], v[58:59], v[130:131] op_sel_hi:[1,0]
	v_pk_mul_f32 v[150:151], v[26:27], v[130:131] op_sel_hi:[1,0]
	v_pk_mul_f32 v[152:153], v[134:135], s[30:31] op_sel_hi:[1,0]
	v_pk_add_f32 v[156:157], v[156:157], 1.0 op_sel_hi:[1,0]
	v_exp_f32_e32 v152, v152
	v_exp_f32_e32 v153, v153
	v_rcp_f32_e32 v156, v156
	v_rcp_f32_e32 v157, v157
	v_pk_mul_f32 v[130:131], v[28:29], v[130:131] op_sel_hi:[1,0]
	v_pk_add_f32 v[152:153], v[152:153], 1.0 op_sel_hi:[1,0]
	s_mov_b64 s[52:53], -1
	v_rcp_f32_e32 v152, v152
	v_rcp_f32_e32 v153, v153
	s_nop 0
	v_pk_mul_f32 v[134:135], v[134:135], v[152:153]
	s_nop 0
	v_pk_mul_f32 v[150:151], v[150:151], v[134:135]
	v_pk_mul_f32 v[134:135], v[154:155], v[156:157]
	s_nop 0
	v_pk_mul_f32 v[152:153], v[130:131], v[134:135]
	v_cvt_pk_bf16_f32 v130, v132, v133
	v_cvt_pk_bf16_f32 v131, v148, v149
	v_cvt_pk_bf16_f32 v132, v150, v151
	v_cvt_pk_bf16_f32 v133, v152, v153
	s_mov_b32 s98, 0x5000
	s_mov_b32 s99, 0x0
	v_lshl_add_u64 v[172:173], v[170:171], 0, s[98:99]
	s_cbranch_vccnz .LBB0_2144
	s_mov_b64 s[52:53], 0
	global_store_dwordx4 v[172:173], v[130:133], off offset:-4096

.LBB0_2146:
	s_waitcnt lgkmcnt(2)
	v_add_f32_e32 v130, v143, v144
	v_fmamk_f32 v130, v130, 0x3a800000, v205
	v_rsq_f32_e32 v130, v130
	s_and_b64 vcc, exec, s[10:11]
	s_mov_b64 s[52:53], -1
	v_mov_b32_e32 v251, v130
	v_pk_mul_f32 v[132:133], v[54:55], v[130:131] op_sel_hi:[1,0]
	v_pk_mul_f32 v[146:147], v[56:57], v[130:131] op_sel_hi:[1,0]
	v_pk_mul_f32 v[144:145], v[132:133], s[30:31] op_sel_hi:[1,0]
	v_pk_mul_f32 v[148:149], v[146:147], s[30:31] op_sel_hi:[1,0]
	v_exp_f32_e32 v144, v144
	v_exp_f32_e32 v145, v145
	v_exp_f32_e32 v148, v148
	v_exp_f32_e32 v149, v149
	v_pk_mul_f32 v[134:135], v[22:23], v[130:131] op_sel_hi:[1,0]
	v_pk_add_f32 v[144:145], v[144:145], 1.0 op_sel_hi:[1,0]
	v_pk_mul_f32 v[150:151], v[52:53], v[130:131] op_sel_hi:[1,0]
	v_rcp_f32_e32 v144, v144
	v_rcp_f32_e32 v145, v145
	v_pk_add_f32 v[148:149], v[148:149], 1.0 op_sel_hi:[1,0]
	v_pk_mul_f32 v[152:153], v[150:151], s[30:31] op_sel_hi:[1,0]
	v_rcp_f32_e32 v148, v148
	v_rcp_f32_e32 v149, v149
	v_pk_mul_f32 v[132:133], v[132:133], v[144:145]
	v_exp_f32_e32 v152, v152
	v_pk_mul_f32 v[132:133], v[134:135], v[132:133]
	v_pk_mul_f32 v[134:135], v[24:25], v[130:131] op_sel_hi:[1,0]
	v_pk_mul_f32 v[144:145], v[146:147], v[148:149]
	v_exp_f32_e32 v153, v153
	v_pk_mul_f32 v[144:145], v[134:135], v[144:145]
	v_pk_mul_f32 v[134:135], v[50:51], v[130:131] op_sel_hi:[1,0]
	v_pk_mul_f32 v[146:147], v[18:19], v[130:131] op_sel_hi:[1,0]
	v_pk_mul_f32 v[148:149], v[134:135], s[30:31] op_sel_hi:[1,0]
	v_pk_add_f32 v[152:153], v[152:153], 1.0 op_sel_hi:[1,0]
	v_exp_f32_e32 v148, v148
	v_exp_f32_e32 v149, v149
	v_rcp_f32_e32 v152, v152
	v_rcp_f32_e32 v153, v153
	v_pk_mul_f32 v[130:131], v[20:21], v[130:131] op_sel_hi:[1,0]
	v_pk_add_f32 v[148:149], v[148:149], 1.0 op_sel_hi:[1,0]
	s_nop 0
	v_rcp_f32_e32 v148, v148
	v_rcp_f32_e32 v149, v149
	s_nop 0
	v_pk_mul_f32 v[134:135], v[134:135], v[148:149]
	s_nop 0
	v_pk_mul_f32 v[146:147], v[146:147], v[134:135]
	v_pk_mul_f32 v[134:135], v[150:151], v[152:153]
	s_nop 0
	v_pk_mul_f32 v[148:149], v[130:131], v[134:135]
	v_cvt_pk_bf16_f32 v130, v132, v133
	v_cvt_pk_bf16_f32 v131, v144, v145
	v_cvt_pk_bf16_f32 v132, v146, v147
	v_cvt_pk_bf16_f32 v133, v148, v149
	s_cbranch_vccnz .LBB0_2148
	s_mov_b64 s[52:53], 0
	global_store_dwordx4 v[172:173], v[130:133], off offset:-2048

.LBB0_2150:
	s_waitcnt lgkmcnt(1)
	v_add_f32_e32 v130, v141, v142
	v_fmamk_f32 v130, v130, 0x3a800000, v205
	v_rsq_f32_e32 v130, v130
	s_and_b64 vcc, exec, s[10:11]
	s_mov_b64 s[52:53], -1
	v_mov_b32_e32 v252, v130
	v_pk_mul_f32 v[132:133], v[46:47], v[130:131] op_sel_hi:[1,0]
	v_pk_mul_f32 v[144:145], v[48:49], v[130:131] op_sel_hi:[1,0]
	v_pk_mul_f32 v[142:143], v[132:133], s[30:31] op_sel_hi:[1,0]
	v_pk_mul_f32 v[146:147], v[144:145], s[30:31] op_sel_hi:[1,0]
	v_exp_f32_e32 v142, v142
	v_exp_f32_e32 v143, v143
	v_exp_f32_e32 v146, v146
	v_exp_f32_e32 v147, v147
	v_pk_mul_f32 v[134:135], v[14:15], v[130:131] op_sel_hi:[1,0]
	v_pk_add_f32 v[142:143], v[142:143], 1.0 op_sel_hi:[1,0]
	v_pk_mul_f32 v[148:149], v[44:45], v[130:131] op_sel_hi:[1,0]
	v_rcp_f32_e32 v142, v142
	v_rcp_f32_e32 v143, v143
	v_pk_add_f32 v[146:147], v[146:147], 1.0 op_sel_hi:[1,0]
	v_pk_mul_f32 v[150:151], v[148:149], s[30:31] op_sel_hi:[1,0]
	v_rcp_f32_e32 v146, v146
	v_rcp_f32_e32 v147, v147
	v_pk_mul_f32 v[132:133], v[132:133], v[142:143]
	v_exp_f32_e32 v150, v150
	v_pk_mul_f32 v[132:133], v[134:135], v[132:133]
	v_pk_mul_f32 v[134:135], v[16:17], v[130:131] op_sel_hi:[1,0]
	v_pk_mul_f32 v[142:143], v[144:145], v[146:147]
	v_exp_f32_e32 v151, v151
	v_pk_mul_f32 v[142:143], v[134:135], v[142:143]
	v_pk_mul_f32 v[134:135], v[42:43], v[130:131] op_sel_hi:[1,0]
	v_pk_mul_f32 v[144:145], v[10:11], v[130:131] op_sel_hi:[1,0]
	v_pk_mul_f32 v[146:147], v[134:135], s[30:31] op_sel_hi:[1,0]
	v_pk_add_f32 v[150:151], v[150:151], 1.0 op_sel_hi:[1,0]
	v_exp_f32_e32 v146, v146
	v_exp_f32_e32 v147, v147
	v_rcp_f32_e32 v150, v150
	v_rcp_f32_e32 v151, v151
	v_pk_mul_f32 v[130:131], v[12:13], v[130:131] op_sel_hi:[1,0]
	v_pk_add_f32 v[146:147], v[146:147], 1.0 op_sel_hi:[1,0]
	s_nop 0
	v_rcp_f32_e32 v146, v146
	v_rcp_f32_e32 v147, v147
	s_nop 0
	v_pk_mul_f32 v[134:135], v[134:135], v[146:147]
	s_nop 0
	v_pk_mul_f32 v[144:145], v[144:145], v[134:135]
	v_pk_mul_f32 v[134:135], v[148:149], v[150:151]
	s_nop 0
	v_pk_mul_f32 v[146:147], v[130:131], v[134:135]
	v_cvt_pk_bf16_f32 v130, v132, v133
	v_cvt_pk_bf16_f32 v131, v142, v143
	v_cvt_pk_bf16_f32 v132, v144, v145
	v_cvt_pk_bf16_f32 v133, v146, v147
	s_cbranch_vccnz .LBB0_2152
	s_mov_b64 s[52:53], 0
	global_store_dwordx4 v[172:173], v[130:133], off

.LBB0_2154:
	s_waitcnt lgkmcnt(0)
	v_add_f32_e32 v130, v139, v140
	v_fmamk_f32 v130, v130, 0x3a800000, v205
	v_rsq_f32_e32 v130, v130
	s_and_b64 vcc, exec, s[10:11]
	s_mov_b64 s[10:11], -1
	v_mov_b32_e32 v253, v130
	v_pk_mul_f32 v[132:133], v[38:39], v[130:131] op_sel_hi:[1,0]
	v_pk_mul_f32 v[142:143], v[40:41], v[130:131] op_sel_hi:[1,0]
	v_pk_mul_f32 v[140:141], v[132:133], s[30:31] op_sel_hi:[1,0]
	v_pk_mul_f32 v[144:145], v[142:143], s[30:31] op_sel_hi:[1,0]
	v_exp_f32_e32 v140, v140
	v_exp_f32_e32 v141, v141
	v_exp_f32_e32 v144, v144
	v_exp_f32_e32 v145, v145
	v_pk_mul_f32 v[134:135], v[6:7], v[130:131] op_sel_hi:[1,0]
	v_pk_add_f32 v[140:141], v[140:141], 1.0 op_sel_hi:[1,0]
	v_pk_mul_f32 v[146:147], v[36:37], v[130:131] op_sel_hi:[1,0]
	v_rcp_f32_e32 v140, v140
	v_rcp_f32_e32 v141, v141
	v_pk_add_f32 v[144:145], v[144:145], 1.0 op_sel_hi:[1,0]
	v_pk_mul_f32 v[148:149], v[146:147], s[30:31] op_sel_hi:[1,0]
	v_rcp_f32_e32 v144, v144
	v_rcp_f32_e32 v145, v145
	v_pk_mul_f32 v[132:133], v[132:133], v[140:141]
	v_exp_f32_e32 v148, v148
	v_pk_mul_f32 v[132:133], v[134:135], v[132:133]
	v_pk_mul_f32 v[134:135], v[8:9], v[130:131] op_sel_hi:[1,0]
	v_pk_mul_f32 v[140:141], v[142:143], v[144:145]
	v_exp_f32_e32 v149, v149
	v_pk_mul_f32 v[140:141], v[134:135], v[140:141]
	v_pk_mul_f32 v[134:135], v[34:35], v[130:131] op_sel_hi:[1,0]
	v_pk_mul_f32 v[142:143], v[2:3], v[130:131] op_sel_hi:[1,0]
	v_pk_mul_f32 v[144:145], v[134:135], s[30:31] op_sel_hi:[1,0]
	v_pk_add_f32 v[148:149], v[148:149], 1.0 op_sel_hi:[1,0]
	v_exp_f32_e32 v144, v144
	v_exp_f32_e32 v145, v145
	v_rcp_f32_e32 v148, v148
	v_rcp_f32_e32 v149, v149
	v_pk_mul_f32 v[130:131], v[4:5], v[130:131] op_sel_hi:[1,0]
	v_pk_add_f32 v[144:145], v[144:145], 1.0 op_sel_hi:[1,0]
	s_nop 0
	v_rcp_f32_e32 v144, v144
	v_rcp_f32_e32 v145, v145
	s_nop 0
	v_pk_mul_f32 v[134:135], v[134:135], v[144:145]
	s_nop 0
	v_pk_mul_f32 v[142:143], v[142:143], v[134:135]
	v_pk_mul_f32 v[134:135], v[146:147], v[148:149]
	s_nop 0
	v_pk_mul_f32 v[144:145], v[130:131], v[134:135]
	v_cvt_pk_bf16_f32 v130, v132, v133
	v_cvt_pk_bf16_f32 v131, v140, v141
	v_cvt_pk_bf16_f32 v132, v142, v143
	v_cvt_pk_bf16_f32 v133, v144, v145
	s_cbranch_vccnz .LBB0_2156
	s_mov_b64 s[10:11], 0
	global_store_dwordx4 v[172:173], v[130:133], off offset:2048
